# no setprio and no redundant lgkmcnt waits in the MFMA segments (barrier, 32 bare MFMAs, barrier)
# speedup vs baseline: 1.0017x; 1.0017x over previous
.Lnb_p1:
	s_add_i32 s7, s4, 0xfff84000
	s_cmp_eq_u32 s6, 28
	s_cselect_b32 s17, s0, s7
	s_cselect_b32 s16, s1, s5
	s_or_b32 s7, s17, 0x4000
	s_mov_b32 m0, s79
	s_nop 0
	buffer_load_dwordx4 v242, s[24:27], s4 offen lds
	s_nop 0
	s_mov_b32 m0, s83
	s_nop 0
	buffer_load_dwordx4 v243, s[24:27], s4 offen lds
	s_waitcnt vmcnt(24)
	s_waitcnt lgkmcnt(0)
	s_barrier
	v_mfma_f32_16x16x32_bf16 v[180:183], v[16:19], v[192:195], 0
	v_mfma_f32_16x16x32_bf16 v[164:167], v[24:27], v[192:195], 0
	v_mfma_f32_16x16x32_bf16 v[148:151], v[16:19], v[200:203], 0
	v_mfma_f32_16x16x32_bf16 v[140:143], v[24:27], v[200:203], 0
	v_mfma_f32_16x16x32_bf16 v[132:135], v[16:19], v[220:223], 0
	v_mfma_f32_16x16x32_bf16 v[124:127], v[24:27], v[220:223], 0
	v_mfma_f32_16x16x32_bf16 v[116:119], v[16:19], v[228:231], 0
	v_mfma_f32_16x16x32_bf16 v[108:111], v[24:27], v[228:231], 0
	v_mfma_f32_16x16x32_bf16 v[180:183], v[20:23], v[196:199], v[180:183]
	v_mfma_f32_16x16x32_bf16 v[164:167], v[28:31], v[196:199], v[164:167]
	v_mfma_f32_16x16x32_bf16 v[148:151], v[20:23], v[204:207], v[148:151]
	v_mfma_f32_16x16x32_bf16 v[140:143], v[28:31], v[204:207], v[140:143]
	v_mfma_f32_16x16x32_bf16 v[132:135], v[20:23], v[224:227], v[132:135]
	v_mfma_f32_16x16x32_bf16 v[124:127], v[28:31], v[224:227], v[124:127]
	v_mfma_f32_16x16x32_bf16 v[116:119], v[20:23], v[246:249], v[116:119]
	v_mfma_f32_16x16x32_bf16 v[108:111], v[28:31], v[246:249], v[108:111]
	v_mfma_f32_16x16x32_bf16 v[172:175], v[152:155], v[192:195], 0
	v_mfma_f32_16x16x32_bf16 v[156:159], v[168:171], v[192:195], 0
	v_mfma_f32_16x16x32_bf16 v[144:147], v[152:155], v[200:203], 0
	v_mfma_f32_16x16x32_bf16 v[136:139], v[168:171], v[200:203], 0
	v_mfma_f32_16x16x32_bf16 v[128:131], v[152:155], v[220:223], 0
	v_mfma_f32_16x16x32_bf16 v[120:123], v[168:171], v[220:223], 0
	v_mfma_f32_16x16x32_bf16 v[112:115], v[152:155], v[228:231], 0
	v_mfma_f32_16x16x32_bf16 v[104:107], v[168:171], v[228:231], 0
	v_mfma_f32_16x16x32_bf16 v[172:175], v[160:163], v[196:199], v[172:175]
	v_mfma_f32_16x16x32_bf16 v[156:159], v[176:179], v[196:199], v[156:159]
	v_mfma_f32_16x16x32_bf16 v[144:147], v[160:163], v[204:207], v[144:147]
	v_mfma_f32_16x16x32_bf16 v[136:139], v[176:179], v[204:207], v[136:139]
	v_mfma_f32_16x16x32_bf16 v[128:131], v[160:163], v[224:227], v[128:131]
	v_mfma_f32_16x16x32_bf16 v[120:123], v[176:179], v[224:227], v[120:123]
	v_mfma_f32_16x16x32_bf16 v[112:115], v[160:163], v[246:249], v[112:115]
	v_mfma_f32_16x16x32_bf16 v[104:107], v[176:179], v[246:249], v[104:107]
	s_barrier
	ds_read_b128 v[192:195], v245 offset:16384
	ds_read_b128 v[196:199], v245 offset:17408
	ds_read_b128 v[200:203], v245 offset:18432
	ds_read_b128 v[204:207], v245 offset:19456
	ds_read_b128 v[220:223], v245 offset:20480
	ds_read_b128 v[224:227], v245 offset:21504
	ds_read_b128 v[228:231], v245 offset:22528
	ds_read_b128 v[246:249], v245 offset:23552
	s_mov_b32 m0, s51
	s_nop 0
	buffer_load_dwordx4 v242, s[56:59], s16 offen lds
	s_add_i32 s18, s16, 0x80000
	s_mov_b32 m0, s52
	s_nop 0
	buffer_load_dwordx4 v243, s[56:59], s16 offen lds
	s_nop 0
	s_mov_b32 m0, s53
	s_nop 0
	buffer_load_dwordx4 v242, s[56:59], s18 offen lds
	s_nop 0
	s_mov_b32 m0, s55
	s_nop 0
	buffer_load_dwordx4 v243, s[56:59], s18 offen lds
	s_nop 0
	s_mov_b32 m0, s31
	s_nop 0
	buffer_load_dwordx4 v242, s[24:27], s17 offen lds
	s_nop 0
	s_mov_b32 m0, s68
	s_nop 0
	buffer_load_dwordx4 v243, s[24:27], s17 offen lds
	s_waitcnt vmcnt(24)
	s_waitcnt lgkmcnt(0)
	s_barrier
	v_mfma_f32_16x16x32_bf16 v[76:79], v[16:19], v[192:195], 0
	v_mfma_f32_16x16x32_bf16 v[68:71], v[24:27], v[192:195], 0
	v_mfma_f32_16x16x32_bf16 v[60:63], v[16:19], v[200:203], 0
	v_mfma_f32_16x16x32_bf16 v[52:55], v[24:27], v[200:203], 0
	v_mfma_f32_16x16x32_bf16 v[44:47], v[16:19], v[220:223], 0
	v_mfma_f32_16x16x32_bf16 v[36:39], v[24:27], v[220:223], 0
	v_mfma_f32_16x16x32_bf16 v[12:15], v[16:19], v[228:231], 0
	v_mfma_f32_16x16x32_bf16 v[4:7], v[24:27], v[228:231], 0
	v_mfma_f32_16x16x32_bf16 v[76:79], v[20:23], v[196:199], v[76:79]
	v_mfma_f32_16x16x32_bf16 v[68:71], v[28:31], v[196:199], v[68:71]
	v_mfma_f32_16x16x32_bf16 v[60:63], v[20:23], v[204:207], v[60:63]
	v_mfma_f32_16x16x32_bf16 v[52:55], v[28:31], v[204:207], v[52:55]
	v_mfma_f32_16x16x32_bf16 v[44:47], v[20:23], v[224:227], v[44:47]
	v_mfma_f32_16x16x32_bf16 v[36:39], v[28:31], v[224:227], v[36:39]
	v_mfma_f32_16x16x32_bf16 v[12:15], v[20:23], v[246:249], v[12:15]
	v_mfma_f32_16x16x32_bf16 v[4:7], v[28:31], v[246:249], v[4:7]
	v_mfma_f32_16x16x32_bf16 v[40:43], v[152:155], v[220:223], 0
	v_mfma_f32_16x16x32_bf16 v[32:35], v[168:171], v[220:223], 0
	v_mfma_f32_16x16x32_bf16 v[8:11], v[152:155], v[228:231], 0
	v_mfma_f32_16x16x32_bf16 v[0:3], v[168:171], v[228:231], 0
	v_mfma_f32_16x16x32_bf16 v[16:19], v[152:155], v[192:195], 0
	v_mfma_f32_16x16x32_bf16 v[20:23], v[168:171], v[192:195], 0
	v_mfma_f32_16x16x32_bf16 v[24:27], v[152:155], v[200:203], 0
	v_mfma_f32_16x16x32_bf16 v[28:31], v[168:171], v[200:203], 0
	v_mfma_f32_16x16x32_bf16 v[40:43], v[160:163], v[224:227], v[40:43]
	v_mfma_f32_16x16x32_bf16 v[32:35], v[176:179], v[224:227], v[32:35]
	v_mfma_f32_16x16x32_bf16 v[8:11], v[160:163], v[246:249], v[8:11]
	v_mfma_f32_16x16x32_bf16 v[0:3], v[176:179], v[246:249], v[0:3]
	v_mfma_f32_16x16x32_bf16 v[16:19], v[160:163], v[196:199], v[16:19]
	v_mfma_f32_16x16x32_bf16 v[20:23], v[176:179], v[196:199], v[20:23]
	v_mfma_f32_16x16x32_bf16 v[24:27], v[160:163], v[204:207], v[24:27]
	v_mfma_f32_16x16x32_bf16 v[28:31], v[176:179], v[204:207], v[28:31]
	s_barrier
	v_add_u32_e32 v72, 0x18000, v83
	v_add_u32_e32 v80, 0x1c000, v83
	ds_read_b128 v[48:51], v72
	ds_read_b128 v[56:59], v72 offset:1024
	ds_read_b128 v[64:67], v72 offset:2048
	ds_read_b128 v[72:75], v72 offset:3072
	ds_read_b128 v[152:155], v80
	ds_read_b128 v[160:163], v80 offset:1024
	ds_read_b128 v[168:171], v80 offset:2048
	ds_read_b128 v[176:179], v80 offset:3072
	ds_read_b128 v[192:195], v245 offset:32768
	ds_read_b128 v[196:199], v245 offset:33792
	ds_read_b128 v[200:203], v245 offset:34816
	ds_read_b128 v[204:207], v245 offset:35840
	ds_read_b128 v[220:223], v245 offset:36864
	ds_read_b128 v[224:227], v245 offset:37888
	ds_read_b128 v[228:231], v245 offset:38912
	ds_read_b128 v[246:249], v245 offset:39936
	s_add_i32 s17, s17, 0x80000
	s_mov_b32 m0, s69
	s_nop 0
	buffer_load_dwordx4 v242, s[24:27], s17 offen lds
	s_nop 0
	s_mov_b32 m0, s70
	s_nop 0
	buffer_load_dwordx4 v243, s[24:27], s17 offen lds
	s_waitcnt vmcnt(8)
	s_waitcnt lgkmcnt(0)
	s_barrier
	v_mfma_f32_16x16x32_bf16 v[180:183], v[48:51], v[192:195], v[180:183]
	v_mfma_f32_16x16x32_bf16 v[164:167], v[64:67], v[192:195], v[164:167]
	v_mfma_f32_16x16x32_bf16 v[148:151], v[48:51], v[200:203], v[148:151]
	v_mfma_f32_16x16x32_bf16 v[140:143], v[64:67], v[200:203], v[140:143]
	v_mfma_f32_16x16x32_bf16 v[132:135], v[48:51], v[220:223], v[132:135]
	v_mfma_f32_16x16x32_bf16 v[124:127], v[64:67], v[220:223], v[124:127]
	v_mfma_f32_16x16x32_bf16 v[116:119], v[48:51], v[228:231], v[116:119]
	v_mfma_f32_16x16x32_bf16 v[108:111], v[64:67], v[228:231], v[108:111]
	v_mfma_f32_16x16x32_bf16 v[180:183], v[56:59], v[196:199], v[180:183]
	v_mfma_f32_16x16x32_bf16 v[164:167], v[72:75], v[196:199], v[164:167]
	v_mfma_f32_16x16x32_bf16 v[148:151], v[56:59], v[204:207], v[148:151]
	v_mfma_f32_16x16x32_bf16 v[140:143], v[72:75], v[204:207], v[140:143]
	v_mfma_f32_16x16x32_bf16 v[132:135], v[56:59], v[224:227], v[132:135]
	v_mfma_f32_16x16x32_bf16 v[124:127], v[72:75], v[224:227], v[124:127]
	v_mfma_f32_16x16x32_bf16 v[116:119], v[56:59], v[246:249], v[116:119]
	v_mfma_f32_16x16x32_bf16 v[108:111], v[72:75], v[246:249], v[108:111]
	v_mfma_f32_16x16x32_bf16 v[172:175], v[152:155], v[192:195], v[172:175]
	v_mfma_f32_16x16x32_bf16 v[156:159], v[168:171], v[192:195], v[156:159]
	v_mfma_f32_16x16x32_bf16 v[144:147], v[152:155], v[200:203], v[144:147]
	v_mfma_f32_16x16x32_bf16 v[136:139], v[168:171], v[200:203], v[136:139]
	v_mfma_f32_16x16x32_bf16 v[128:131], v[152:155], v[220:223], v[128:131]
	v_mfma_f32_16x16x32_bf16 v[120:123], v[168:171], v[220:223], v[120:123]
	v_mfma_f32_16x16x32_bf16 v[112:115], v[152:155], v[228:231], v[112:115]
	v_mfma_f32_16x16x32_bf16 v[104:107], v[168:171], v[228:231], v[104:107]
	v_mfma_f32_16x16x32_bf16 v[172:175], v[160:163], v[196:199], v[172:175]
	v_mfma_f32_16x16x32_bf16 v[156:159], v[176:179], v[196:199], v[156:159]
	v_mfma_f32_16x16x32_bf16 v[144:147], v[160:163], v[204:207], v[144:147]
	v_mfma_f32_16x16x32_bf16 v[136:139], v[176:179], v[204:207], v[136:139]
	v_mfma_f32_16x16x32_bf16 v[128:131], v[160:163], v[224:227], v[128:131]
	v_mfma_f32_16x16x32_bf16 v[120:123], v[176:179], v[224:227], v[120:123]
	v_mfma_f32_16x16x32_bf16 v[112:115], v[160:163], v[246:249], v[112:115]
	v_mfma_f32_16x16x32_bf16 v[104:107], v[176:179], v[246:249], v[104:107]
	s_barrier
	ds_read_b128 v[192:195], v245 offset:49152
	ds_read_b128 v[196:199], v245 offset:50176
	ds_read_b128 v[200:203], v245 offset:51200
	ds_read_b128 v[204:207], v245 offset:52224
	ds_read_b128 v[220:223], v245 offset:53248
	ds_read_b128 v[224:227], v245 offset:54272
	ds_read_b128 v[228:231], v245 offset:55296
	ds_read_b128 v[246:249], v245 offset:56320
	s_or_b32 s17, s16, 0x4000
	s_mov_b32 m0, s73
	s_nop 0
	buffer_load_dwordx4 v242, s[56:59], s17 offen lds
	s_add_i32 s16, s16, 0x84000
	s_mov_b32 m0, s74
	s_nop 0
	buffer_load_dwordx4 v243, s[56:59], s17 offen lds
	s_nop 0
	s_mov_b32 m0, s77
	s_nop 0
	buffer_load_dwordx4 v242, s[56:59], s16 offen lds
	s_nop 0
	s_mov_b32 m0, s78
	s_nop 0
	buffer_load_dwordx4 v243, s[56:59], s16 offen lds
	s_nop 0
	s_mov_b32 m0, s75
	s_nop 0
	buffer_load_dwordx4 v242, s[24:27], s7 offen lds
	s_nop 0
	s_mov_b32 m0, s76
	s_nop 0
	buffer_load_dwordx4 v243, s[24:27], s7 offen lds
	s_waitcnt vmcnt(8)
	s_waitcnt lgkmcnt(0)
	s_barrier
	v_mfma_f32_16x16x32_bf16 v[76:79], v[48:51], v[192:195], v[76:79]
	v_mfma_f32_16x16x32_bf16 v[68:71], v[64:67], v[192:195], v[68:71]
	v_mfma_f32_16x16x32_bf16 v[60:63], v[48:51], v[200:203], v[60:63]
	v_mfma_f32_16x16x32_bf16 v[52:55], v[64:67], v[200:203], v[52:55]
	v_mfma_f32_16x16x32_bf16 v[44:47], v[48:51], v[220:223], v[44:47]
	v_mfma_f32_16x16x32_bf16 v[36:39], v[64:67], v[220:223], v[36:39]
	v_mfma_f32_16x16x32_bf16 v[12:15], v[48:51], v[228:231], v[12:15]
	v_mfma_f32_16x16x32_bf16 v[4:7], v[64:67], v[228:231], v[4:7]
	v_mfma_f32_16x16x32_bf16 v[76:79], v[56:59], v[196:199], v[76:79]
	v_mfma_f32_16x16x32_bf16 v[68:71], v[72:75], v[196:199], v[68:71]
	v_mfma_f32_16x16x32_bf16 v[60:63], v[56:59], v[204:207], v[60:63]
	v_mfma_f32_16x16x32_bf16 v[52:55], v[72:75], v[204:207], v[52:55]
	v_mfma_f32_16x16x32_bf16 v[44:47], v[56:59], v[224:227], v[44:47]
	v_mfma_f32_16x16x32_bf16 v[36:39], v[72:75], v[224:227], v[36:39]
	v_mfma_f32_16x16x32_bf16 v[12:15], v[56:59], v[246:249], v[12:15]
	v_mfma_f32_16x16x32_bf16 v[4:7], v[72:75], v[246:249], v[4:7]
	v_mfma_f32_16x16x32_bf16 v[16:19], v[152:155], v[192:195], v[16:19]
	v_mfma_f32_16x16x32_bf16 v[72:75], v[160:163], v[196:199], v[16:19]
	v_mfma_f32_16x16x32_bf16 v[16:19], v[168:171], v[192:195], v[20:23]
	v_mfma_f32_16x16x32_bf16 v[64:67], v[176:179], v[196:199], v[16:19]
	v_mfma_f32_16x16x32_bf16 v[16:19], v[152:155], v[200:203], v[24:27]
	v_mfma_f32_16x16x32_bf16 v[56:59], v[160:163], v[204:207], v[16:19]
	v_mfma_f32_16x16x32_bf16 v[16:19], v[168:171], v[200:203], v[28:31]
	v_mfma_f32_16x16x32_bf16 v[48:51], v[176:179], v[204:207], v[16:19]
	v_mfma_f32_16x16x32_bf16 v[16:19], v[152:155], v[220:223], v[40:43]
	v_mfma_f32_16x16x32_bf16 v[40:43], v[160:163], v[224:227], v[16:19]
	v_mfma_f32_16x16x32_bf16 v[16:19], v[168:171], v[220:223], v[32:35]
	v_mfma_f32_16x16x32_bf16 v[8:11], v[152:155], v[228:231], v[8:11]
	v_mfma_f32_16x16x32_bf16 v[0:3], v[168:171], v[228:231], v[0:3]
	v_mfma_f32_16x16x32_bf16 v[32:35], v[176:179], v[224:227], v[16:19]
	v_mfma_f32_16x16x32_bf16 v[8:11], v[160:163], v[246:249], v[8:11]
	v_mfma_f32_16x16x32_bf16 v[0:3], v[176:179], v[246:249], v[0:3]
	s_barrier
	s_add_i32 s6, s6, 2
	s_add_i32 s4, s4, 0x8000
	s_add_i32 s5, s5, 0x8000
.LBB0_143:
	v_add_u32_e32 v28, 0x10000, v83
	v_add_u32_e32 v80, 0x14000, v83
	ds_read_b128 v[16:19], v28
	ds_read_b128 v[20:23], v28 offset:1024
	ds_read_b128 v[24:27], v28 offset:2048
	ds_read_b128 v[28:31], v28 offset:3072
	ds_read_b128 v[152:155], v80
	ds_read_b128 v[160:163], v80 offset:1024
	ds_read_b128 v[168:171], v80 offset:2048
	ds_read_b128 v[176:179], v80 offset:3072
	s_add_i32 s7, s4, 0xfff84000
	s_cmp_eq_u32 s6, 28
	s_cselect_b32 s17, s0, s7
	s_cselect_b32 s16, s1, s5
	s_or_b32 s7, s17, 0x4000
	ds_read_b128 v[192:195], v245
	ds_read_b128 v[196:199], v245 offset:1024
	ds_read_b128 v[200:203], v245 offset:2048
	ds_read_b128 v[204:207], v245 offset:3072
	ds_read_b128 v[220:223], v245 offset:4096
	ds_read_b128 v[224:227], v245 offset:5120
	ds_read_b128 v[228:231], v245 offset:6144
	ds_read_b128 v[246:249], v245 offset:7168
	s_mov_b32 m0, s79
	s_nop 0
	buffer_load_dwordx4 v242, s[24:27], s4 offen lds
	s_nop 0
	s_mov_b32 m0, s83
	s_nop 0
	buffer_load_dwordx4 v243, s[24:27], s4 offen lds
	s_waitcnt vmcnt(8)
	s_waitcnt lgkmcnt(0)
	s_barrier
	v_mfma_f32_16x16x32_bf16 v[180:183], v[16:19], v[192:195], v[180:183]
	v_mfma_f32_16x16x32_bf16 v[164:167], v[24:27], v[192:195], v[164:167]
	v_mfma_f32_16x16x32_bf16 v[148:151], v[16:19], v[200:203], v[148:151]
	v_mfma_f32_16x16x32_bf16 v[140:143], v[24:27], v[200:203], v[140:143]
	v_mfma_f32_16x16x32_bf16 v[132:135], v[16:19], v[220:223], v[132:135]
	v_mfma_f32_16x16x32_bf16 v[124:127], v[24:27], v[220:223], v[124:127]
	v_mfma_f32_16x16x32_bf16 v[116:119], v[16:19], v[228:231], v[116:119]
	v_mfma_f32_16x16x32_bf16 v[108:111], v[24:27], v[228:231], v[108:111]
	v_mfma_f32_16x16x32_bf16 v[180:183], v[20:23], v[196:199], v[180:183]
	v_mfma_f32_16x16x32_bf16 v[164:167], v[28:31], v[196:199], v[164:167]
	v_mfma_f32_16x16x32_bf16 v[148:151], v[20:23], v[204:207], v[148:151]
	v_mfma_f32_16x16x32_bf16 v[140:143], v[28:31], v[204:207], v[140:143]
	v_mfma_f32_16x16x32_bf16 v[132:135], v[20:23], v[224:227], v[132:135]
	v_mfma_f32_16x16x32_bf16 v[124:127], v[28:31], v[224:227], v[124:127]
	v_mfma_f32_16x16x32_bf16 v[116:119], v[20:23], v[246:249], v[116:119]
	v_mfma_f32_16x16x32_bf16 v[108:111], v[28:31], v[246:249], v[108:111]
	v_mfma_f32_16x16x32_bf16 v[172:175], v[152:155], v[192:195], v[172:175]
	v_mfma_f32_16x16x32_bf16 v[156:159], v[168:171], v[192:195], v[156:159]
	v_mfma_f32_16x16x32_bf16 v[144:147], v[152:155], v[200:203], v[144:147]
	v_mfma_f32_16x16x32_bf16 v[136:139], v[168:171], v[200:203], v[136:139]
	v_mfma_f32_16x16x32_bf16 v[128:131], v[152:155], v[220:223], v[128:131]
	v_mfma_f32_16x16x32_bf16 v[120:123], v[168:171], v[220:223], v[120:123]
	v_mfma_f32_16x16x32_bf16 v[112:115], v[152:155], v[228:231], v[112:115]
	v_mfma_f32_16x16x32_bf16 v[104:107], v[168:171], v[228:231], v[104:107]
	v_mfma_f32_16x16x32_bf16 v[172:175], v[160:163], v[196:199], v[172:175]
	v_mfma_f32_16x16x32_bf16 v[156:159], v[176:179], v[196:199], v[156:159]
	v_mfma_f32_16x16x32_bf16 v[144:147], v[160:163], v[204:207], v[144:147]
	v_mfma_f32_16x16x32_bf16 v[136:139], v[176:179], v[204:207], v[136:139]
	v_mfma_f32_16x16x32_bf16 v[128:131], v[160:163], v[224:227], v[128:131]
	v_mfma_f32_16x16x32_bf16 v[120:123], v[176:179], v[224:227], v[120:123]
	v_mfma_f32_16x16x32_bf16 v[112:115], v[160:163], v[246:249], v[112:115]
	v_mfma_f32_16x16x32_bf16 v[104:107], v[176:179], v[246:249], v[104:107]
	s_barrier
	ds_read_b128 v[192:195], v245 offset:16384
	ds_read_b128 v[196:199], v245 offset:17408
	ds_read_b128 v[200:203], v245 offset:18432
	ds_read_b128 v[204:207], v245 offset:19456
	ds_read_b128 v[220:223], v245 offset:20480
	ds_read_b128 v[224:227], v245 offset:21504
	ds_read_b128 v[228:231], v245 offset:22528
	ds_read_b128 v[246:249], v245 offset:23552
	s_mov_b32 m0, s51
	s_nop 0
	buffer_load_dwordx4 v242, s[56:59], s16 offen lds
	s_add_i32 s18, s16, 0x80000
	s_mov_b32 m0, s52
	s_nop 0
	buffer_load_dwordx4 v243, s[56:59], s16 offen lds
	s_nop 0
	s_mov_b32 m0, s53
	s_nop 0
	buffer_load_dwordx4 v242, s[56:59], s18 offen lds
	s_nop 0
	s_mov_b32 m0, s55
	s_nop 0
	buffer_load_dwordx4 v243, s[56:59], s18 offen lds
	s_nop 0
	s_mov_b32 m0, s31
	s_nop 0
	buffer_load_dwordx4 v242, s[24:27], s17 offen lds
	s_nop 0
	s_mov_b32 m0, s68
	s_nop 0
	buffer_load_dwordx4 v243, s[24:27], s17 offen lds
	s_waitcnt vmcnt(8)
	s_waitcnt lgkmcnt(0)
	s_barrier
	v_mfma_f32_16x16x32_bf16 v[76:79], v[16:19], v[192:195], v[76:79]
	v_mfma_f32_16x16x32_bf16 v[68:71], v[24:27], v[192:195], v[68:71]
	v_mfma_f32_16x16x32_bf16 v[60:63], v[16:19], v[200:203], v[60:63]
	v_mfma_f32_16x16x32_bf16 v[52:55], v[24:27], v[200:203], v[52:55]
	v_mfma_f32_16x16x32_bf16 v[44:47], v[16:19], v[220:223], v[44:47]
	v_mfma_f32_16x16x32_bf16 v[36:39], v[24:27], v[220:223], v[36:39]
	v_mfma_f32_16x16x32_bf16 v[12:15], v[16:19], v[228:231], v[12:15]
	v_mfma_f32_16x16x32_bf16 v[4:7], v[24:27], v[228:231], v[4:7]
	v_mfma_f32_16x16x32_bf16 v[76:79], v[20:23], v[196:199], v[76:79]
	v_mfma_f32_16x16x32_bf16 v[68:71], v[28:31], v[196:199], v[68:71]
	v_mfma_f32_16x16x32_bf16 v[60:63], v[20:23], v[204:207], v[60:63]
	v_mfma_f32_16x16x32_bf16 v[52:55], v[28:31], v[204:207], v[52:55]
	v_mfma_f32_16x16x32_bf16 v[44:47], v[20:23], v[224:227], v[44:47]
	v_mfma_f32_16x16x32_bf16 v[36:39], v[28:31], v[224:227], v[36:39]
	v_mfma_f32_16x16x32_bf16 v[12:15], v[20:23], v[246:249], v[12:15]
	v_mfma_f32_16x16x32_bf16 v[4:7], v[28:31], v[246:249], v[4:7]
	v_mfma_f32_16x16x32_bf16 v[40:43], v[152:155], v[220:223], v[40:43]
	v_mfma_f32_16x16x32_bf16 v[32:35], v[168:171], v[220:223], v[32:35]
	v_mfma_f32_16x16x32_bf16 v[8:11], v[152:155], v[228:231], v[8:11]
	v_mfma_f32_16x16x32_bf16 v[0:3], v[168:171], v[228:231], v[0:3]
	v_mfma_f32_16x16x32_bf16 v[16:19], v[152:155], v[192:195], v[72:75]
	v_mfma_f32_16x16x32_bf16 v[20:23], v[168:171], v[192:195], v[64:67]
	v_mfma_f32_16x16x32_bf16 v[24:27], v[152:155], v[200:203], v[56:59]
	v_mfma_f32_16x16x32_bf16 v[28:31], v[168:171], v[200:203], v[48:51]
	v_mfma_f32_16x16x32_bf16 v[40:43], v[160:163], v[224:227], v[40:43]
	v_mfma_f32_16x16x32_bf16 v[32:35], v[176:179], v[224:227], v[32:35]
	v_mfma_f32_16x16x32_bf16 v[8:11], v[160:163], v[246:249], v[8:11]
	v_mfma_f32_16x16x32_bf16 v[0:3], v[176:179], v[246:249], v[0:3]
	v_mfma_f32_16x16x32_bf16 v[16:19], v[160:163], v[196:199], v[16:19]
	v_mfma_f32_16x16x32_bf16 v[20:23], v[176:179], v[196:199], v[20:23]
	v_mfma_f32_16x16x32_bf16 v[24:27], v[160:163], v[204:207], v[24:27]
	v_mfma_f32_16x16x32_bf16 v[28:31], v[176:179], v[204:207], v[28:31]
	s_barrier
	v_add_u32_e32 v72, 0x18000, v83
	v_add_u32_e32 v80, 0x1c000, v83
	ds_read_b128 v[48:51], v72
	ds_read_b128 v[56:59], v72 offset:1024
	ds_read_b128 v[64:67], v72 offset:2048
	ds_read_b128 v[72:75], v72 offset:3072
	ds_read_b128 v[152:155], v80
	ds_read_b128 v[160:163], v80 offset:1024
	ds_read_b128 v[168:171], v80 offset:2048
	ds_read_b128 v[176:179], v80 offset:3072
	ds_read_b128 v[192:195], v245 offset:32768
	ds_read_b128 v[196:199], v245 offset:33792
	ds_read_b128 v[200:203], v245 offset:34816
	ds_read_b128 v[204:207], v245 offset:35840
	ds_read_b128 v[220:223], v245 offset:36864
	ds_read_b128 v[224:227], v245 offset:37888
	ds_read_b128 v[228:231], v245 offset:38912
	ds_read_b128 v[246:249], v245 offset:39936
	s_add_i32 s17, s17, 0x80000
	s_mov_b32 m0, s69
	s_nop 0
	buffer_load_dwordx4 v242, s[24:27], s17 offen lds
	s_nop 0
	s_mov_b32 m0, s70
	s_nop 0
	buffer_load_dwordx4 v243, s[24:27], s17 offen lds
	s_waitcnt vmcnt(8)
	s_waitcnt lgkmcnt(0)
	s_barrier
	v_mfma_f32_16x16x32_bf16 v[180:183], v[48:51], v[192:195], v[180:183]
	v_mfma_f32_16x16x32_bf16 v[164:167], v[64:67], v[192:195], v[164:167]
	v_mfma_f32_16x16x32_bf16 v[148:151], v[48:51], v[200:203], v[148:151]
	v_mfma_f32_16x16x32_bf16 v[140:143], v[64:67], v[200:203], v[140:143]
	v_mfma_f32_16x16x32_bf16 v[132:135], v[48:51], v[220:223], v[132:135]
	v_mfma_f32_16x16x32_bf16 v[124:127], v[64:67], v[220:223], v[124:127]
	v_mfma_f32_16x16x32_bf16 v[116:119], v[48:51], v[228:231], v[116:119]
	v_mfma_f32_16x16x32_bf16 v[108:111], v[64:67], v[228:231], v[108:111]
	v_mfma_f32_16x16x32_bf16 v[180:183], v[56:59], v[196:199], v[180:183]
	v_mfma_f32_16x16x32_bf16 v[164:167], v[72:75], v[196:199], v[164:167]
	v_mfma_f32_16x16x32_bf16 v[148:151], v[56:59], v[204:207], v[148:151]
	v_mfma_f32_16x16x32_bf16 v[140:143], v[72:75], v[204:207], v[140:143]
	v_mfma_f32_16x16x32_bf16 v[132:135], v[56:59], v[224:227], v[132:135]
	v_mfma_f32_16x16x32_bf16 v[124:127], v[72:75], v[224:227], v[124:127]
	v_mfma_f32_16x16x32_bf16 v[116:119], v[56:59], v[246:249], v[116:119]
	v_mfma_f32_16x16x32_bf16 v[108:111], v[72:75], v[246:249], v[108:111]
	v_mfma_f32_16x16x32_bf16 v[172:175], v[152:155], v[192:195], v[172:175]
	v_mfma_f32_16x16x32_bf16 v[156:159], v[168:171], v[192:195], v[156:159]
	v_mfma_f32_16x16x32_bf16 v[144:147], v[152:155], v[200:203], v[144:147]
	v_mfma_f32_16x16x32_bf16 v[136:139], v[168:171], v[200:203], v[136:139]
	v_mfma_f32_16x16x32_bf16 v[128:131], v[152:155], v[220:223], v[128:131]
	v_mfma_f32_16x16x32_bf16 v[120:123], v[168:171], v[220:223], v[120:123]
	v_mfma_f32_16x16x32_bf16 v[112:115], v[152:155], v[228:231], v[112:115]
	v_mfma_f32_16x16x32_bf16 v[104:107], v[168:171], v[228:231], v[104:107]
	v_mfma_f32_16x16x32_bf16 v[172:175], v[160:163], v[196:199], v[172:175]
	v_mfma_f32_16x16x32_bf16 v[156:159], v[176:179], v[196:199], v[156:159]
	v_mfma_f32_16x16x32_bf16 v[144:147], v[160:163], v[204:207], v[144:147]
	v_mfma_f32_16x16x32_bf16 v[136:139], v[176:179], v[204:207], v[136:139]
	v_mfma_f32_16x16x32_bf16 v[128:131], v[160:163], v[224:227], v[128:131]
	v_mfma_f32_16x16x32_bf16 v[120:123], v[176:179], v[224:227], v[120:123]
	v_mfma_f32_16x16x32_bf16 v[112:115], v[160:163], v[246:249], v[112:115]
	v_mfma_f32_16x16x32_bf16 v[104:107], v[176:179], v[246:249], v[104:107]
	s_barrier
	ds_read_b128 v[192:195], v245 offset:49152
	ds_read_b128 v[196:199], v245 offset:50176
	ds_read_b128 v[200:203], v245 offset:51200
	ds_read_b128 v[204:207], v245 offset:52224
	ds_read_b128 v[220:223], v245 offset:53248
	ds_read_b128 v[224:227], v245 offset:54272
	ds_read_b128 v[228:231], v245 offset:55296
	ds_read_b128 v[246:249], v245 offset:56320
	s_or_b32 s17, s16, 0x4000
	s_mov_b32 m0, s73
	s_nop 0
	buffer_load_dwordx4 v242, s[56:59], s17 offen lds
	s_add_i32 s16, s16, 0x84000
	s_mov_b32 m0, s74
	s_nop 0
	buffer_load_dwordx4 v243, s[56:59], s17 offen lds
	s_nop 0
	s_mov_b32 m0, s77
	s_nop 0
	buffer_load_dwordx4 v242, s[56:59], s16 offen lds
	s_nop 0
	s_mov_b32 m0, s78
	s_nop 0
	buffer_load_dwordx4 v243, s[56:59], s16 offen lds
	s_nop 0
	s_mov_b32 m0, s75
	s_nop 0
	buffer_load_dwordx4 v242, s[24:27], s7 offen lds
	s_nop 0
	s_mov_b32 m0, s76
	s_nop 0
	buffer_load_dwordx4 v243, s[24:27], s7 offen lds
	s_waitcnt vmcnt(8)
	s_waitcnt lgkmcnt(0)
	s_barrier
	v_mfma_f32_16x16x32_bf16 v[76:79], v[48:51], v[192:195], v[76:79]
	v_mfma_f32_16x16x32_bf16 v[68:71], v[64:67], v[192:195], v[68:71]
	v_mfma_f32_16x16x32_bf16 v[60:63], v[48:51], v[200:203], v[60:63]
	v_mfma_f32_16x16x32_bf16 v[52:55], v[64:67], v[200:203], v[52:55]
	v_mfma_f32_16x16x32_bf16 v[44:47], v[48:51], v[220:223], v[44:47]
	v_mfma_f32_16x16x32_bf16 v[36:39], v[64:67], v[220:223], v[36:39]
	v_mfma_f32_16x16x32_bf16 v[12:15], v[48:51], v[228:231], v[12:15]
	v_mfma_f32_16x16x32_bf16 v[4:7], v[64:67], v[228:231], v[4:7]
	v_mfma_f32_16x16x32_bf16 v[76:79], v[56:59], v[196:199], v[76:79]
	v_mfma_f32_16x16x32_bf16 v[68:71], v[72:75], v[196:199], v[68:71]
	v_mfma_f32_16x16x32_bf16 v[60:63], v[56:59], v[204:207], v[60:63]
	v_mfma_f32_16x16x32_bf16 v[52:55], v[72:75], v[204:207], v[52:55]
	v_mfma_f32_16x16x32_bf16 v[44:47], v[56:59], v[224:227], v[44:47]
	v_mfma_f32_16x16x32_bf16 v[36:39], v[72:75], v[224:227], v[36:39]
	v_mfma_f32_16x16x32_bf16 v[12:15], v[56:59], v[246:249], v[12:15]
	v_mfma_f32_16x16x32_bf16 v[4:7], v[72:75], v[246:249], v[4:7]
	v_mfma_f32_16x16x32_bf16 v[16:19], v[152:155], v[192:195], v[16:19]
	v_mfma_f32_16x16x32_bf16 v[72:75], v[160:163], v[196:199], v[16:19]
	v_mfma_f32_16x16x32_bf16 v[16:19], v[168:171], v[192:195], v[20:23]
	v_mfma_f32_16x16x32_bf16 v[64:67], v[176:179], v[196:199], v[16:19]
	v_mfma_f32_16x16x32_bf16 v[16:19], v[152:155], v[200:203], v[24:27]
	v_mfma_f32_16x16x32_bf16 v[56:59], v[160:163], v[204:207], v[16:19]
	v_mfma_f32_16x16x32_bf16 v[16:19], v[168:171], v[200:203], v[28:31]
	v_mfma_f32_16x16x32_bf16 v[48:51], v[176:179], v[204:207], v[16:19]
	v_mfma_f32_16x16x32_bf16 v[16:19], v[152:155], v[220:223], v[40:43]
	v_mfma_f32_16x16x32_bf16 v[40:43], v[160:163], v[224:227], v[16:19]
	v_mfma_f32_16x16x32_bf16 v[16:19], v[168:171], v[220:223], v[32:35]
	v_mfma_f32_16x16x32_bf16 v[8:11], v[152:155], v[228:231], v[8:11]
	v_mfma_f32_16x16x32_bf16 v[0:3], v[168:171], v[228:231], v[0:3]
	v_mfma_f32_16x16x32_bf16 v[32:35], v[176:179], v[224:227], v[16:19]
	v_mfma_f32_16x16x32_bf16 v[8:11], v[160:163], v[246:249], v[8:11]
	v_mfma_f32_16x16x32_bf16 v[0:3], v[176:179], v[246:249], v[0:3]
	s_barrier
	s_add_i32 s6, s6, 2
	s_add_i32 s4, s4, 0x8000
	s_add_i32 s5, s5, 0x8000
	s_cmp_gt_u32 s6, 29
	s_cbranch_scc0 .LBB0_143

.LBB0_594:
	v_add_u32_e32 v80, 0x10000, v226
	ds_read_b128 v[152:155], v80
	ds_read_b128 v[156:159], v80 offset:1024
	ds_read_b128 v[160:163], v80 offset:2048
	ds_read_b128 v[164:167], v80 offset:3072
	v_add_u32_e32 v80, 0x14000, v226
	ds_read_b128 v[168:171], v80
	ds_read_b128 v[172:175], v80 offset:1024
	ds_read_b128 v[176:179], v80 offset:2048
	ds_read_b128 v[180:183], v80 offset:3072
	s_add_i32 s97, s96, s39
	s_add_i32 s94, s97, 0x8000
	s_add_i32 s95, s93, s39
	s_cmp_eq_u32 s39, 0x78000
	s_cselect_b32 s36, vcc_lo, s94
	s_cselect_b32 s95, vcc_hi, s95
	s_or_b32 s94, s36, 0x4000
	ds_read_b128 v[184:187], v227
	ds_read_b128 v[188:191], v227 offset:1024
	ds_read_b128 v[192:195], v227 offset:2048
	ds_read_b128 v[196:199], v227 offset:3072
	ds_read_b128 v[200:203], v227 offset:4096
	ds_read_b128 v[204:207], v227 offset:5120
	ds_read_b128 v[228:231], v227 offset:6144
	ds_read_b128 v[240:243], v227 offset:7168
	s_add_i32 s97, s97, 0x84000
	s_mov_b32 m0, s85
	s_nop 0
	buffer_load_dwordx4 v224, s[60:63], s97 offen lds
	s_nop 0
	s_mov_b32 m0, s86
	s_nop 0
	buffer_load_dwordx4 v225, s[60:63], s97 offen lds
	s_waitcnt vmcnt(8)
	s_waitcnt lgkmcnt(0)
	s_barrier
	v_mfma_f32_16x16x32_bf16 v[148:151], v[152:155], v[184:187], v[148:151]
	v_mfma_f32_16x16x32_bf16 v[144:147], v[160:163], v[184:187], v[144:147]
	v_mfma_f32_16x16x32_bf16 v[132:135], v[152:155], v[192:195], v[132:135]
	v_mfma_f32_16x16x32_bf16 v[128:131], v[160:163], v[192:195], v[128:131]
	v_mfma_f32_16x16x32_bf16 v[116:119], v[152:155], v[200:203], v[116:119]
	v_mfma_f32_16x16x32_bf16 v[112:115], v[160:163], v[200:203], v[112:115]
	v_mfma_f32_16x16x32_bf16 v[76:79], v[152:155], v[228:231], v[76:79]
	v_mfma_f32_16x16x32_bf16 v[72:75], v[160:163], v[228:231], v[72:75]
	v_mfma_f32_16x16x32_bf16 v[148:151], v[156:159], v[188:191], v[148:151]
	v_mfma_f32_16x16x32_bf16 v[144:147], v[164:167], v[188:191], v[144:147]
	v_mfma_f32_16x16x32_bf16 v[132:135], v[156:159], v[196:199], v[132:135]
	v_mfma_f32_16x16x32_bf16 v[128:131], v[164:167], v[196:199], v[128:131]
	v_mfma_f32_16x16x32_bf16 v[116:119], v[156:159], v[204:207], v[116:119]
	v_mfma_f32_16x16x32_bf16 v[112:115], v[164:167], v[204:207], v[112:115]
	v_mfma_f32_16x16x32_bf16 v[76:79], v[156:159], v[240:243], v[76:79]
	v_mfma_f32_16x16x32_bf16 v[72:75], v[164:167], v[240:243], v[72:75]
	v_mfma_f32_16x16x32_bf16 v[140:143], v[168:171], v[184:187], v[140:143]
	v_mfma_f32_16x16x32_bf16 v[136:139], v[176:179], v[184:187], v[136:139]
	v_mfma_f32_16x16x32_bf16 v[124:127], v[168:171], v[192:195], v[124:127]
	v_mfma_f32_16x16x32_bf16 v[120:123], v[176:179], v[192:195], v[120:123]
	v_mfma_f32_16x16x32_bf16 v[108:111], v[168:171], v[200:203], v[108:111]
	v_mfma_f32_16x16x32_bf16 v[104:107], v[176:179], v[200:203], v[104:107]
	v_mfma_f32_16x16x32_bf16 v[68:71], v[168:171], v[228:231], v[68:71]
	v_mfma_f32_16x16x32_bf16 v[64:67], v[176:179], v[228:231], v[64:67]
	v_mfma_f32_16x16x32_bf16 v[140:143], v[172:175], v[188:191], v[140:143]
	v_mfma_f32_16x16x32_bf16 v[136:139], v[180:183], v[188:191], v[136:139]
	v_mfma_f32_16x16x32_bf16 v[124:127], v[172:175], v[196:199], v[124:127]
	v_mfma_f32_16x16x32_bf16 v[120:123], v[180:183], v[196:199], v[120:123]
	v_mfma_f32_16x16x32_bf16 v[108:111], v[172:175], v[204:207], v[108:111]
	v_mfma_f32_16x16x32_bf16 v[104:107], v[180:183], v[204:207], v[104:107]
	v_mfma_f32_16x16x32_bf16 v[68:71], v[172:175], v[240:243], v[68:71]
	v_mfma_f32_16x16x32_bf16 v[64:67], v[180:183], v[240:243], v[64:67]
	s_barrier
	ds_read_b128 v[184:187], v227 offset:16384
	ds_read_b128 v[188:191], v227 offset:17408
	ds_read_b128 v[192:195], v227 offset:18432
	ds_read_b128 v[196:199], v227 offset:19456
	ds_read_b128 v[200:203], v227 offset:20480
	ds_read_b128 v[204:207], v227 offset:21504
	ds_read_b128 v[228:231], v227 offset:22528
	ds_read_b128 v[240:243], v227 offset:23552
	s_mov_b32 m0, s34
	s_nop 0
	buffer_load_dwordx4 v224, s[48:51], s95 offen lds
	s_add_i32 s97, s95, 0x80000
	s_mov_b32 m0, s55
	s_nop 0
	buffer_load_dwordx4 v225, s[48:51], s95 offen lds
	s_nop 0
	s_mov_b32 m0, s72
	s_nop 0
	buffer_load_dwordx4 v224, s[48:51], s97 offen lds
	s_nop 0
	s_mov_b32 m0, s73
	s_nop 0
	buffer_load_dwordx4 v225, s[48:51], s97 offen lds
	s_nop 0
	s_mov_b32 m0, s31
	s_nop 0
	buffer_load_dwordx4 v224, s[60:63], s36 offen lds
	s_nop 0
	s_mov_b32 m0, s74
	s_nop 0
	buffer_load_dwordx4 v225, s[60:63], s36 offen lds
	s_waitcnt vmcnt(8)
	s_waitcnt lgkmcnt(0)
	s_barrier
	v_mfma_f32_16x16x32_bf16 v[60:63], v[152:155], v[184:187], v[60:63]
	v_mfma_f32_16x16x32_bf16 v[56:59], v[160:163], v[184:187], v[56:59]
	v_mfma_f32_16x16x32_bf16 v[44:47], v[152:155], v[192:195], v[44:47]
	v_mfma_f32_16x16x32_bf16 v[40:43], v[160:163], v[192:195], v[40:43]
	v_mfma_f32_16x16x32_bf16 v[28:31], v[152:155], v[200:203], v[28:31]
	v_mfma_f32_16x16x32_bf16 v[24:27], v[160:163], v[200:203], v[24:27]
	v_mfma_f32_16x16x32_bf16 v[12:15], v[152:155], v[228:231], v[12:15]
	v_mfma_f32_16x16x32_bf16 v[8:11], v[160:163], v[228:231], v[8:11]
	v_mfma_f32_16x16x32_bf16 v[60:63], v[156:159], v[188:191], v[60:63]
	v_mfma_f32_16x16x32_bf16 v[56:59], v[164:167], v[188:191], v[56:59]
	v_mfma_f32_16x16x32_bf16 v[44:47], v[156:159], v[196:199], v[44:47]
	v_mfma_f32_16x16x32_bf16 v[40:43], v[164:167], v[196:199], v[40:43]
	v_mfma_f32_16x16x32_bf16 v[28:31], v[156:159], v[204:207], v[28:31]
	v_mfma_f32_16x16x32_bf16 v[24:27], v[164:167], v[204:207], v[24:27]
	v_mfma_f32_16x16x32_bf16 v[12:15], v[156:159], v[240:243], v[12:15]
	v_mfma_f32_16x16x32_bf16 v[8:11], v[164:167], v[240:243], v[8:11]
	v_mfma_f32_16x16x32_bf16 v[52:55], v[168:171], v[184:187], v[52:55]
	v_mfma_f32_16x16x32_bf16 v[48:51], v[176:179], v[184:187], v[48:51]
	v_mfma_f32_16x16x32_bf16 v[36:39], v[168:171], v[192:195], v[36:39]
	v_mfma_f32_16x16x32_bf16 v[32:35], v[176:179], v[192:195], v[32:35]
	v_mfma_f32_16x16x32_bf16 v[20:23], v[168:171], v[200:203], v[20:23]
	v_mfma_f32_16x16x32_bf16 v[16:19], v[176:179], v[200:203], v[16:19]
	v_mfma_f32_16x16x32_bf16 v[4:7], v[168:171], v[228:231], v[4:7]
	v_mfma_f32_16x16x32_bf16 v[0:3], v[176:179], v[228:231], v[0:3]
	v_mfma_f32_16x16x32_bf16 v[52:55], v[172:175], v[188:191], v[52:55]
	v_mfma_f32_16x16x32_bf16 v[48:51], v[180:183], v[188:191], v[48:51]
	v_mfma_f32_16x16x32_bf16 v[36:39], v[172:175], v[196:199], v[36:39]
	v_mfma_f32_16x16x32_bf16 v[32:35], v[180:183], v[196:199], v[32:35]
	v_mfma_f32_16x16x32_bf16 v[20:23], v[172:175], v[204:207], v[20:23]
	v_mfma_f32_16x16x32_bf16 v[16:19], v[180:183], v[204:207], v[16:19]
	v_mfma_f32_16x16x32_bf16 v[4:7], v[172:175], v[240:243], v[4:7]
	v_mfma_f32_16x16x32_bf16 v[0:3], v[180:183], v[240:243], v[0:3]
	s_barrier
	v_add_u32_e32 v80, 0x18000, v226
	ds_read_b128 v[152:155], v80
	ds_read_b128 v[156:159], v80 offset:1024
	ds_read_b128 v[160:163], v80 offset:2048
	ds_read_b128 v[164:167], v80 offset:3072
	v_add_u32_e32 v80, 0x1c000, v226
	ds_read_b128 v[168:171], v80
	ds_read_b128 v[172:175], v80 offset:1024
	ds_read_b128 v[176:179], v80 offset:2048
	ds_read_b128 v[180:183], v80 offset:3072
	ds_read_b128 v[184:187], v227 offset:32768
	ds_read_b128 v[188:191], v227 offset:33792
	ds_read_b128 v[192:195], v227 offset:34816
	ds_read_b128 v[196:199], v227 offset:35840
	ds_read_b128 v[200:203], v227 offset:36864
	ds_read_b128 v[204:207], v227 offset:37888
	ds_read_b128 v[228:231], v227 offset:38912
	ds_read_b128 v[240:243], v227 offset:39936
	s_add_i32 s36, s36, 0x80000
	s_mov_b32 m0, s75
	s_nop 0
	buffer_load_dwordx4 v224, s[60:63], s36 offen lds
	s_nop 0
	s_mov_b32 m0, s76
	s_nop 0
	buffer_load_dwordx4 v225, s[60:63], s36 offen lds
	s_waitcnt vmcnt(8)
	s_waitcnt lgkmcnt(0)
	s_barrier
	v_mfma_f32_16x16x32_bf16 v[148:151], v[152:155], v[184:187], v[148:151]
	v_mfma_f32_16x16x32_bf16 v[144:147], v[160:163], v[184:187], v[144:147]
	v_mfma_f32_16x16x32_bf16 v[132:135], v[152:155], v[192:195], v[132:135]
	v_mfma_f32_16x16x32_bf16 v[128:131], v[160:163], v[192:195], v[128:131]
	v_mfma_f32_16x16x32_bf16 v[116:119], v[152:155], v[200:203], v[116:119]
	v_mfma_f32_16x16x32_bf16 v[112:115], v[160:163], v[200:203], v[112:115]
	v_mfma_f32_16x16x32_bf16 v[76:79], v[152:155], v[228:231], v[76:79]
	v_mfma_f32_16x16x32_bf16 v[72:75], v[160:163], v[228:231], v[72:75]
	v_mfma_f32_16x16x32_bf16 v[148:151], v[156:159], v[188:191], v[148:151]
	v_mfma_f32_16x16x32_bf16 v[144:147], v[164:167], v[188:191], v[144:147]
	v_mfma_f32_16x16x32_bf16 v[132:135], v[156:159], v[196:199], v[132:135]
	v_mfma_f32_16x16x32_bf16 v[128:131], v[164:167], v[196:199], v[128:131]
	v_mfma_f32_16x16x32_bf16 v[116:119], v[156:159], v[204:207], v[116:119]
	v_mfma_f32_16x16x32_bf16 v[112:115], v[164:167], v[204:207], v[112:115]
	v_mfma_f32_16x16x32_bf16 v[76:79], v[156:159], v[240:243], v[76:79]
	v_mfma_f32_16x16x32_bf16 v[72:75], v[164:167], v[240:243], v[72:75]
	v_mfma_f32_16x16x32_bf16 v[140:143], v[168:171], v[184:187], v[140:143]
	v_mfma_f32_16x16x32_bf16 v[136:139], v[176:179], v[184:187], v[136:139]
	v_mfma_f32_16x16x32_bf16 v[124:127], v[168:171], v[192:195], v[124:127]
	v_mfma_f32_16x16x32_bf16 v[120:123], v[176:179], v[192:195], v[120:123]
	v_mfma_f32_16x16x32_bf16 v[108:111], v[168:171], v[200:203], v[108:111]
	v_mfma_f32_16x16x32_bf16 v[104:107], v[176:179], v[200:203], v[104:107]
	v_mfma_f32_16x16x32_bf16 v[68:71], v[168:171], v[228:231], v[68:71]
	v_mfma_f32_16x16x32_bf16 v[64:67], v[176:179], v[228:231], v[64:67]
	v_mfma_f32_16x16x32_bf16 v[140:143], v[172:175], v[188:191], v[140:143]
	v_mfma_f32_16x16x32_bf16 v[136:139], v[180:183], v[188:191], v[136:139]
	v_mfma_f32_16x16x32_bf16 v[124:127], v[172:175], v[196:199], v[124:127]
	v_mfma_f32_16x16x32_bf16 v[120:123], v[180:183], v[196:199], v[120:123]
	v_mfma_f32_16x16x32_bf16 v[108:111], v[172:175], v[204:207], v[108:111]
	v_mfma_f32_16x16x32_bf16 v[104:107], v[180:183], v[204:207], v[104:107]
	v_mfma_f32_16x16x32_bf16 v[68:71], v[172:175], v[240:243], v[68:71]
	v_mfma_f32_16x16x32_bf16 v[64:67], v[180:183], v[240:243], v[64:67]
	s_barrier
	ds_read_b128 v[184:187], v227 offset:49152
	ds_read_b128 v[188:191], v227 offset:50176
	ds_read_b128 v[192:195], v227 offset:51200
	ds_read_b128 v[196:199], v227 offset:52224
	ds_read_b128 v[200:203], v227 offset:53248
	ds_read_b128 v[204:207], v227 offset:54272
	ds_read_b128 v[228:231], v227 offset:55296
	ds_read_b128 v[240:243], v227 offset:56320
	s_or_b32 s36, s95, 0x4000
	s_mov_b32 m0, s77
	s_nop 0
	buffer_load_dwordx4 v224, s[48:51], s36 offen lds
	s_nop 0
	s_mov_b32 m0, s78
	s_nop 0
	buffer_load_dwordx4 v225, s[48:51], s36 offen lds
	s_add_i32 s36, s95, 0x84000
	s_mov_b32 m0, s83
	s_nop 0
	buffer_load_dwordx4 v224, s[48:51], s36 offen lds
	s_nop 0
	s_mov_b32 m0, s84
	s_nop 0
	buffer_load_dwordx4 v225, s[48:51], s36 offen lds
	s_nop 0
	s_mov_b32 m0, s79
	s_nop 0
	buffer_load_dwordx4 v224, s[60:63], s94 offen lds
	s_nop 0
	s_mov_b32 m0, s82
	s_nop 0
	buffer_load_dwordx4 v225, s[60:63], s94 offen lds
	s_waitcnt vmcnt(8)
	s_waitcnt lgkmcnt(0)
	s_barrier
	v_mfma_f32_16x16x32_bf16 v[60:63], v[152:155], v[184:187], v[60:63]
	v_mfma_f32_16x16x32_bf16 v[56:59], v[160:163], v[184:187], v[56:59]
	v_mfma_f32_16x16x32_bf16 v[44:47], v[152:155], v[192:195], v[44:47]
	v_mfma_f32_16x16x32_bf16 v[40:43], v[160:163], v[192:195], v[40:43]
	v_mfma_f32_16x16x32_bf16 v[28:31], v[152:155], v[200:203], v[28:31]
	v_mfma_f32_16x16x32_bf16 v[24:27], v[160:163], v[200:203], v[24:27]
	v_mfma_f32_16x16x32_bf16 v[12:15], v[152:155], v[228:231], v[12:15]
	v_mfma_f32_16x16x32_bf16 v[8:11], v[160:163], v[228:231], v[8:11]
	v_mfma_f32_16x16x32_bf16 v[60:63], v[156:159], v[188:191], v[60:63]
	v_mfma_f32_16x16x32_bf16 v[56:59], v[164:167], v[188:191], v[56:59]
	v_mfma_f32_16x16x32_bf16 v[44:47], v[156:159], v[196:199], v[44:47]
	v_mfma_f32_16x16x32_bf16 v[40:43], v[164:167], v[196:199], v[40:43]
	v_mfma_f32_16x16x32_bf16 v[28:31], v[156:159], v[204:207], v[28:31]
	v_mfma_f32_16x16x32_bf16 v[24:27], v[164:167], v[204:207], v[24:27]
	v_mfma_f32_16x16x32_bf16 v[12:15], v[156:159], v[240:243], v[12:15]
	v_mfma_f32_16x16x32_bf16 v[8:11], v[164:167], v[240:243], v[8:11]
	v_mfma_f32_16x16x32_bf16 v[52:55], v[168:171], v[184:187], v[52:55]
	v_mfma_f32_16x16x32_bf16 v[48:51], v[176:179], v[184:187], v[48:51]
	v_mfma_f32_16x16x32_bf16 v[36:39], v[168:171], v[192:195], v[36:39]
	v_mfma_f32_16x16x32_bf16 v[32:35], v[176:179], v[192:195], v[32:35]
	v_mfma_f32_16x16x32_bf16 v[20:23], v[168:171], v[200:203], v[20:23]
	v_mfma_f32_16x16x32_bf16 v[16:19], v[176:179], v[200:203], v[16:19]
	v_mfma_f32_16x16x32_bf16 v[4:7], v[168:171], v[228:231], v[4:7]
	v_mfma_f32_16x16x32_bf16 v[0:3], v[176:179], v[228:231], v[0:3]
	v_mfma_f32_16x16x32_bf16 v[52:55], v[172:175], v[188:191], v[52:55]
	v_mfma_f32_16x16x32_bf16 v[48:51], v[180:183], v[188:191], v[48:51]
	v_mfma_f32_16x16x32_bf16 v[36:39], v[172:175], v[196:199], v[36:39]
	v_mfma_f32_16x16x32_bf16 v[32:35], v[180:183], v[196:199], v[32:35]
	v_mfma_f32_16x16x32_bf16 v[20:23], v[172:175], v[204:207], v[20:23]
	v_mfma_f32_16x16x32_bf16 v[16:19], v[180:183], v[204:207], v[16:19]
	v_mfma_f32_16x16x32_bf16 v[4:7], v[172:175], v[240:243], v[4:7]
	v_mfma_f32_16x16x32_bf16 v[0:3], v[180:183], v[240:243], v[0:3]
	s_barrier
	s_add_i32 s38, s38, 2
	s_add_i32 s39, s39, 0x8000
	s_cmp_gt_u32 s38, 29
	s_cbranch_scc1 .LBB0_597

.Lnb_p4:
	s_add_i32 s11, s8, 0xfff84000
	s_cmp_eq_u32 s10, 28
	s_cselect_b32 s13, s6, s11
	s_cselect_b32 s12, s7, s9
	s_or_b32 s11, s13, 0x4000
	s_mov_b32 m0, s89
	s_nop 0
	buffer_load_dwordx4 v220, s[64:67], s8 offen lds
	s_nop 0
	s_mov_b32 m0, s91
	s_nop 0
	buffer_load_dwordx4 v221, s[64:67], s8 offen lds
	s_waitcnt vmcnt(24)
	s_waitcnt lgkmcnt(0)
	s_barrier
	v_mfma_f32_16x16x32_bf16 v[164:167], v[128:131], v[184:187], 0
	v_mfma_f32_16x16x32_bf16 v[160:163], v[152:155], v[184:187], 0
	v_mfma_f32_16x16x32_bf16 v[136:139], v[128:131], v[192:195], 0
	v_mfma_f32_16x16x32_bf16 v[132:135], v[152:155], v[192:195], 0
	v_mfma_f32_16x16x32_bf16 v[116:119], v[128:131], v[200:203], 0
	v_mfma_f32_16x16x32_bf16 v[112:115], v[152:155], v[200:203], 0
	v_mfma_f32_16x16x32_bf16 v[76:79], v[128:131], v[224:227], 0
	v_mfma_f32_16x16x32_bf16 v[72:75], v[152:155], v[224:227], 0
	v_mfma_f32_16x16x32_bf16 v[164:167], v[140:143], v[188:191], v[164:167]
	v_mfma_f32_16x16x32_bf16 v[160:163], v[156:159], v[188:191], v[160:163]
	v_mfma_f32_16x16x32_bf16 v[136:139], v[140:143], v[196:199], v[136:139]
	v_mfma_f32_16x16x32_bf16 v[132:135], v[156:159], v[196:199], v[132:135]
	v_mfma_f32_16x16x32_bf16 v[116:119], v[140:143], v[204:207], v[116:119]
	v_mfma_f32_16x16x32_bf16 v[112:115], v[156:159], v[204:207], v[112:115]
	v_mfma_f32_16x16x32_bf16 v[76:79], v[140:143], v[228:231], v[76:79]
	v_mfma_f32_16x16x32_bf16 v[72:75], v[156:159], v[228:231], v[72:75]
	v_mfma_f32_16x16x32_bf16 v[148:151], v[168:171], v[184:187], 0
	v_mfma_f32_16x16x32_bf16 v[144:147], v[176:179], v[184:187], 0
	v_mfma_f32_16x16x32_bf16 v[124:127], v[168:171], v[192:195], 0
	v_mfma_f32_16x16x32_bf16 v[120:123], v[176:179], v[192:195], 0
	v_mfma_f32_16x16x32_bf16 v[108:111], v[168:171], v[200:203], 0
	v_mfma_f32_16x16x32_bf16 v[104:107], v[176:179], v[200:203], 0
	v_mfma_f32_16x16x32_bf16 v[68:71], v[168:171], v[224:227], 0
	v_mfma_f32_16x16x32_bf16 v[64:67], v[176:179], v[224:227], 0
	v_mfma_f32_16x16x32_bf16 v[148:151], v[172:175], v[188:191], v[148:151]
	v_mfma_f32_16x16x32_bf16 v[144:147], v[180:183], v[188:191], v[144:147]
	v_mfma_f32_16x16x32_bf16 v[124:127], v[172:175], v[196:199], v[124:127]
	v_mfma_f32_16x16x32_bf16 v[120:123], v[180:183], v[196:199], v[120:123]
	v_mfma_f32_16x16x32_bf16 v[108:111], v[172:175], v[204:207], v[108:111]
	v_mfma_f32_16x16x32_bf16 v[104:107], v[180:183], v[204:207], v[104:107]
	v_mfma_f32_16x16x32_bf16 v[68:71], v[172:175], v[228:231], v[68:71]
	v_mfma_f32_16x16x32_bf16 v[64:67], v[180:183], v[228:231], v[64:67]
	s_barrier
	ds_read_b128 v[184:187], v223 offset:16384
	ds_read_b128 v[188:191], v223 offset:17408
	ds_read_b128 v[192:195], v223 offset:18432
	ds_read_b128 v[196:199], v223 offset:19456
	ds_read_b128 v[200:203], v223 offset:20480
	ds_read_b128 v[204:207], v223 offset:21504
	ds_read_b128 v[224:227], v223 offset:22528
	ds_read_b128 v[228:231], v223 offset:23552
	s_mov_b32 m0, s55
	s_nop 0
	buffer_load_dwordx4 v220, s[48:51], s12 offen lds
	s_add_i32 s14, s12, 0x80000
	s_mov_b32 m0, s76
	s_nop 0
	buffer_load_dwordx4 v221, s[48:51], s12 offen lds
	s_nop 0
	s_mov_b32 m0, s77
	s_nop 0
	buffer_load_dwordx4 v220, s[48:51], s14 offen lds
	s_nop 0
	s_mov_b32 m0, s78
	s_nop 0
	buffer_load_dwordx4 v221, s[48:51], s14 offen lds
	s_nop 0
	s_mov_b32 m0, s31
	s_nop 0
	buffer_load_dwordx4 v220, s[64:67], s13 offen lds
	s_nop 0
	s_mov_b32 m0, s79
	s_nop 0
	buffer_load_dwordx4 v221, s[64:67], s13 offen lds
	s_waitcnt vmcnt(24)
	s_waitcnt lgkmcnt(0)
	s_barrier
	v_mfma_f32_16x16x32_bf16 v[60:63], v[128:131], v[184:187], 0
	v_mfma_f32_16x16x32_bf16 v[56:59], v[152:155], v[184:187], 0
	v_mfma_f32_16x16x32_bf16 v[44:47], v[128:131], v[192:195], 0
	v_mfma_f32_16x16x32_bf16 v[40:43], v[152:155], v[192:195], 0
	v_mfma_f32_16x16x32_bf16 v[28:31], v[128:131], v[200:203], 0
	v_mfma_f32_16x16x32_bf16 v[24:27], v[152:155], v[200:203], 0
	v_mfma_f32_16x16x32_bf16 v[12:15], v[128:131], v[224:227], 0
	v_mfma_f32_16x16x32_bf16 v[8:11], v[152:155], v[224:227], 0
	v_mfma_f32_16x16x32_bf16 v[60:63], v[140:143], v[188:191], v[60:63]
	v_mfma_f32_16x16x32_bf16 v[56:59], v[156:159], v[188:191], v[56:59]
	v_mfma_f32_16x16x32_bf16 v[44:47], v[140:143], v[196:199], v[44:47]
	v_mfma_f32_16x16x32_bf16 v[40:43], v[156:159], v[196:199], v[40:43]
	v_mfma_f32_16x16x32_bf16 v[28:31], v[140:143], v[204:207], v[28:31]
	v_mfma_f32_16x16x32_bf16 v[24:27], v[156:159], v[204:207], v[24:27]
	v_mfma_f32_16x16x32_bf16 v[12:15], v[140:143], v[228:231], v[12:15]
	v_mfma_f32_16x16x32_bf16 v[8:11], v[156:159], v[228:231], v[8:11]
	v_mfma_f32_16x16x32_bf16 v[52:55], v[168:171], v[184:187], 0
	v_mfma_f32_16x16x32_bf16 v[48:51], v[176:179], v[184:187], 0
	v_mfma_f32_16x16x32_bf16 v[36:39], v[168:171], v[192:195], 0
	v_mfma_f32_16x16x32_bf16 v[32:35], v[176:179], v[192:195], 0
	v_mfma_f32_16x16x32_bf16 v[20:23], v[168:171], v[200:203], 0
	v_mfma_f32_16x16x32_bf16 v[16:19], v[176:179], v[200:203], 0
	v_mfma_f32_16x16x32_bf16 v[4:7], v[168:171], v[224:227], 0
	v_mfma_f32_16x16x32_bf16 v[0:3], v[176:179], v[224:227], 0
	v_mfma_f32_16x16x32_bf16 v[52:55], v[172:175], v[188:191], v[52:55]
	v_mfma_f32_16x16x32_bf16 v[48:51], v[180:183], v[188:191], v[48:51]
	v_mfma_f32_16x16x32_bf16 v[36:39], v[172:175], v[196:199], v[36:39]
	v_mfma_f32_16x16x32_bf16 v[32:35], v[180:183], v[196:199], v[32:35]
	v_mfma_f32_16x16x32_bf16 v[20:23], v[172:175], v[204:207], v[20:23]
	v_mfma_f32_16x16x32_bf16 v[16:19], v[180:183], v[204:207], v[16:19]
	v_mfma_f32_16x16x32_bf16 v[4:7], v[172:175], v[228:231], v[4:7]
	v_mfma_f32_16x16x32_bf16 v[0:3], v[180:183], v[228:231], v[0:3]
	s_barrier
	v_add_u32_e32 v156, 0x18000, v222
	v_add_u32_e32 v180, 0x1c000, v222
	ds_read_b128 v[128:131], v156
	ds_read_b128 v[140:143], v156 offset:1024
	ds_read_b128 v[152:155], v156 offset:2048
	ds_read_b128 v[156:159], v156 offset:3072
	ds_read_b128 v[168:171], v180
	ds_read_b128 v[172:175], v180 offset:1024
	ds_read_b128 v[176:179], v180 offset:2048
	ds_read_b128 v[180:183], v180 offset:3072
	ds_read_b128 v[184:187], v223 offset:32768
	ds_read_b128 v[188:191], v223 offset:33792
	ds_read_b128 v[192:195], v223 offset:34816
	ds_read_b128 v[196:199], v223 offset:35840
	ds_read_b128 v[200:203], v223 offset:36864
	ds_read_b128 v[204:207], v223 offset:37888
	ds_read_b128 v[224:227], v223 offset:38912
	ds_read_b128 v[228:231], v223 offset:39936
	s_add_i32 s13, s13, 0x80000
	s_mov_b32 m0, s82
	s_nop 0
	buffer_load_dwordx4 v220, s[64:67], s13 offen lds
	s_nop 0
	s_mov_b32 m0, s83
	s_nop 0
	buffer_load_dwordx4 v221, s[64:67], s13 offen lds
	s_waitcnt vmcnt(8)
	s_waitcnt lgkmcnt(0)
	s_barrier
	v_mfma_f32_16x16x32_bf16 v[164:167], v[128:131], v[184:187], v[164:167]
	v_mfma_f32_16x16x32_bf16 v[160:163], v[152:155], v[184:187], v[160:163]
	v_mfma_f32_16x16x32_bf16 v[136:139], v[128:131], v[192:195], v[136:139]
	v_mfma_f32_16x16x32_bf16 v[132:135], v[152:155], v[192:195], v[132:135]
	v_mfma_f32_16x16x32_bf16 v[116:119], v[128:131], v[200:203], v[116:119]
	v_mfma_f32_16x16x32_bf16 v[112:115], v[152:155], v[200:203], v[112:115]
	v_mfma_f32_16x16x32_bf16 v[76:79], v[128:131], v[224:227], v[76:79]
	v_mfma_f32_16x16x32_bf16 v[72:75], v[152:155], v[224:227], v[72:75]
	v_mfma_f32_16x16x32_bf16 v[164:167], v[140:143], v[188:191], v[164:167]
	v_mfma_f32_16x16x32_bf16 v[160:163], v[156:159], v[188:191], v[160:163]
	v_mfma_f32_16x16x32_bf16 v[136:139], v[140:143], v[196:199], v[136:139]
	v_mfma_f32_16x16x32_bf16 v[132:135], v[156:159], v[196:199], v[132:135]
	v_mfma_f32_16x16x32_bf16 v[116:119], v[140:143], v[204:207], v[116:119]
	v_mfma_f32_16x16x32_bf16 v[112:115], v[156:159], v[204:207], v[112:115]
	v_mfma_f32_16x16x32_bf16 v[76:79], v[140:143], v[228:231], v[76:79]
	v_mfma_f32_16x16x32_bf16 v[72:75], v[156:159], v[228:231], v[72:75]
	v_mfma_f32_16x16x32_bf16 v[148:151], v[168:171], v[184:187], v[148:151]
	v_mfma_f32_16x16x32_bf16 v[144:147], v[176:179], v[184:187], v[144:147]
	v_mfma_f32_16x16x32_bf16 v[124:127], v[168:171], v[192:195], v[124:127]
	v_mfma_f32_16x16x32_bf16 v[120:123], v[176:179], v[192:195], v[120:123]
	v_mfma_f32_16x16x32_bf16 v[108:111], v[168:171], v[200:203], v[108:111]
	v_mfma_f32_16x16x32_bf16 v[104:107], v[176:179], v[200:203], v[104:107]
	v_mfma_f32_16x16x32_bf16 v[68:71], v[168:171], v[224:227], v[68:71]
	v_mfma_f32_16x16x32_bf16 v[64:67], v[176:179], v[224:227], v[64:67]
	v_mfma_f32_16x16x32_bf16 v[148:151], v[172:175], v[188:191], v[148:151]
	v_mfma_f32_16x16x32_bf16 v[144:147], v[180:183], v[188:191], v[144:147]
	v_mfma_f32_16x16x32_bf16 v[124:127], v[172:175], v[196:199], v[124:127]
	v_mfma_f32_16x16x32_bf16 v[120:123], v[180:183], v[196:199], v[120:123]
	v_mfma_f32_16x16x32_bf16 v[108:111], v[172:175], v[204:207], v[108:111]
	v_mfma_f32_16x16x32_bf16 v[104:107], v[180:183], v[204:207], v[104:107]
	v_mfma_f32_16x16x32_bf16 v[68:71], v[172:175], v[228:231], v[68:71]
	v_mfma_f32_16x16x32_bf16 v[64:67], v[180:183], v[228:231], v[64:67]
	s_barrier
	ds_read_b128 v[184:187], v223 offset:49152
	ds_read_b128 v[188:191], v223 offset:50176
	ds_read_b128 v[192:195], v223 offset:51200
	ds_read_b128 v[196:199], v223 offset:52224
	ds_read_b128 v[200:203], v223 offset:53248
	ds_read_b128 v[204:207], v223 offset:54272
	ds_read_b128 v[224:227], v223 offset:55296
	ds_read_b128 v[228:231], v223 offset:56320
	s_or_b32 s13, s12, 0x4000
	s_mov_b32 m0, s34
	s_nop 0
	buffer_load_dwordx4 v220, s[48:51], s13 offen lds
	s_add_i32 s12, s12, 0x84000
	s_mov_b32 m0, s84
	s_nop 0
	buffer_load_dwordx4 v221, s[48:51], s13 offen lds
	s_nop 0
	s_mov_b32 m0, s87
	s_nop 0
	buffer_load_dwordx4 v220, s[48:51], s12 offen lds
	s_nop 0
	s_mov_b32 m0, s88
	s_nop 0
	buffer_load_dwordx4 v221, s[48:51], s12 offen lds
	s_nop 0
	s_mov_b32 m0, s85
	s_nop 0
	buffer_load_dwordx4 v220, s[64:67], s11 offen lds
	s_nop 0
	s_mov_b32 m0, s86
	s_nop 0
	buffer_load_dwordx4 v221, s[64:67], s11 offen lds
	s_waitcnt vmcnt(8)
	s_waitcnt lgkmcnt(0)
	s_barrier
	v_mfma_f32_16x16x32_bf16 v[60:63], v[128:131], v[184:187], v[60:63]
	v_mfma_f32_16x16x32_bf16 v[56:59], v[152:155], v[184:187], v[56:59]
	v_mfma_f32_16x16x32_bf16 v[44:47], v[128:131], v[192:195], v[44:47]
	v_mfma_f32_16x16x32_bf16 v[40:43], v[152:155], v[192:195], v[40:43]
	v_mfma_f32_16x16x32_bf16 v[28:31], v[128:131], v[200:203], v[28:31]
	v_mfma_f32_16x16x32_bf16 v[24:27], v[152:155], v[200:203], v[24:27]
	v_mfma_f32_16x16x32_bf16 v[12:15], v[128:131], v[224:227], v[12:15]
	v_mfma_f32_16x16x32_bf16 v[8:11], v[152:155], v[224:227], v[8:11]
	v_mfma_f32_16x16x32_bf16 v[60:63], v[140:143], v[188:191], v[60:63]
	v_mfma_f32_16x16x32_bf16 v[56:59], v[156:159], v[188:191], v[56:59]
	v_mfma_f32_16x16x32_bf16 v[44:47], v[140:143], v[196:199], v[44:47]
	v_mfma_f32_16x16x32_bf16 v[40:43], v[156:159], v[196:199], v[40:43]
	v_mfma_f32_16x16x32_bf16 v[28:31], v[140:143], v[204:207], v[28:31]
	v_mfma_f32_16x16x32_bf16 v[24:27], v[156:159], v[204:207], v[24:27]
	v_mfma_f32_16x16x32_bf16 v[12:15], v[140:143], v[228:231], v[12:15]
	v_mfma_f32_16x16x32_bf16 v[8:11], v[156:159], v[228:231], v[8:11]
	v_mfma_f32_16x16x32_bf16 v[52:55], v[168:171], v[184:187], v[52:55]
	v_mfma_f32_16x16x32_bf16 v[48:51], v[176:179], v[184:187], v[48:51]
	v_mfma_f32_16x16x32_bf16 v[36:39], v[168:171], v[192:195], v[36:39]
	v_mfma_f32_16x16x32_bf16 v[32:35], v[176:179], v[192:195], v[32:35]
	v_mfma_f32_16x16x32_bf16 v[20:23], v[168:171], v[200:203], v[20:23]
	v_mfma_f32_16x16x32_bf16 v[16:19], v[176:179], v[200:203], v[16:19]
	v_mfma_f32_16x16x32_bf16 v[4:7], v[168:171], v[224:227], v[4:7]
	v_mfma_f32_16x16x32_bf16 v[0:3], v[176:179], v[224:227], v[0:3]
	v_mfma_f32_16x16x32_bf16 v[52:55], v[172:175], v[188:191], v[52:55]
	v_mfma_f32_16x16x32_bf16 v[48:51], v[180:183], v[188:191], v[48:51]
	v_mfma_f32_16x16x32_bf16 v[36:39], v[172:175], v[196:199], v[36:39]
	v_mfma_f32_16x16x32_bf16 v[32:35], v[180:183], v[196:199], v[32:35]
	v_mfma_f32_16x16x32_bf16 v[20:23], v[172:175], v[204:207], v[20:23]
	v_mfma_f32_16x16x32_bf16 v[16:19], v[180:183], v[204:207], v[16:19]
	v_mfma_f32_16x16x32_bf16 v[4:7], v[172:175], v[228:231], v[4:7]
	v_mfma_f32_16x16x32_bf16 v[0:3], v[180:183], v[228:231], v[0:3]
	s_barrier
	s_add_i32 s10, s10, 2
	s_add_i32 s8, s8, 0x8000
	s_add_i32 s9, s9, 0x8000
.LBB0_691:
	v_add_u32_e32 v156, 0x10000, v222
	v_add_u32_e32 v180, 0x14000, v222
	ds_read_b128 v[128:131], v156
	ds_read_b128 v[140:143], v156 offset:1024
	ds_read_b128 v[152:155], v156 offset:2048
	ds_read_b128 v[156:159], v156 offset:3072
	ds_read_b128 v[168:171], v180
	ds_read_b128 v[172:175], v180 offset:1024
	ds_read_b128 v[176:179], v180 offset:2048
	ds_read_b128 v[180:183], v180 offset:3072
	s_add_i32 s11, s8, 0xfff84000
	s_cmp_eq_u32 s10, 28
	s_cselect_b32 s13, s6, s11
	s_cselect_b32 s12, s7, s9
	s_or_b32 s11, s13, 0x4000
	ds_read_b128 v[184:187], v223
	ds_read_b128 v[188:191], v223 offset:1024
	ds_read_b128 v[192:195], v223 offset:2048
	ds_read_b128 v[196:199], v223 offset:3072
	ds_read_b128 v[200:203], v223 offset:4096
	ds_read_b128 v[204:207], v223 offset:5120
	ds_read_b128 v[224:227], v223 offset:6144
	ds_read_b128 v[228:231], v223 offset:7168
	s_mov_b32 m0, s89
	s_nop 0
	buffer_load_dwordx4 v220, s[64:67], s8 offen lds
	s_nop 0
	s_mov_b32 m0, s91
	s_nop 0
	buffer_load_dwordx4 v221, s[64:67], s8 offen lds
	s_waitcnt vmcnt(8)
	s_waitcnt lgkmcnt(0)
	s_barrier
	v_mfma_f32_16x16x32_bf16 v[164:167], v[128:131], v[184:187], v[164:167]
	v_mfma_f32_16x16x32_bf16 v[160:163], v[152:155], v[184:187], v[160:163]
	v_mfma_f32_16x16x32_bf16 v[136:139], v[128:131], v[192:195], v[136:139]
	v_mfma_f32_16x16x32_bf16 v[132:135], v[152:155], v[192:195], v[132:135]
	v_mfma_f32_16x16x32_bf16 v[116:119], v[128:131], v[200:203], v[116:119]
	v_mfma_f32_16x16x32_bf16 v[112:115], v[152:155], v[200:203], v[112:115]
	v_mfma_f32_16x16x32_bf16 v[76:79], v[128:131], v[224:227], v[76:79]
	v_mfma_f32_16x16x32_bf16 v[72:75], v[152:155], v[224:227], v[72:75]
	v_mfma_f32_16x16x32_bf16 v[164:167], v[140:143], v[188:191], v[164:167]
	v_mfma_f32_16x16x32_bf16 v[160:163], v[156:159], v[188:191], v[160:163]
	v_mfma_f32_16x16x32_bf16 v[136:139], v[140:143], v[196:199], v[136:139]
	v_mfma_f32_16x16x32_bf16 v[132:135], v[156:159], v[196:199], v[132:135]
	v_mfma_f32_16x16x32_bf16 v[116:119], v[140:143], v[204:207], v[116:119]
	v_mfma_f32_16x16x32_bf16 v[112:115], v[156:159], v[204:207], v[112:115]
	v_mfma_f32_16x16x32_bf16 v[76:79], v[140:143], v[228:231], v[76:79]
	v_mfma_f32_16x16x32_bf16 v[72:75], v[156:159], v[228:231], v[72:75]
	v_mfma_f32_16x16x32_bf16 v[148:151], v[168:171], v[184:187], v[148:151]
	v_mfma_f32_16x16x32_bf16 v[144:147], v[176:179], v[184:187], v[144:147]
	v_mfma_f32_16x16x32_bf16 v[124:127], v[168:171], v[192:195], v[124:127]
	v_mfma_f32_16x16x32_bf16 v[120:123], v[176:179], v[192:195], v[120:123]
	v_mfma_f32_16x16x32_bf16 v[108:111], v[168:171], v[200:203], v[108:111]
	v_mfma_f32_16x16x32_bf16 v[104:107], v[176:179], v[200:203], v[104:107]
	v_mfma_f32_16x16x32_bf16 v[68:71], v[168:171], v[224:227], v[68:71]
	v_mfma_f32_16x16x32_bf16 v[64:67], v[176:179], v[224:227], v[64:67]
	v_mfma_f32_16x16x32_bf16 v[148:151], v[172:175], v[188:191], v[148:151]
	v_mfma_f32_16x16x32_bf16 v[144:147], v[180:183], v[188:191], v[144:147]
	v_mfma_f32_16x16x32_bf16 v[124:127], v[172:175], v[196:199], v[124:127]
	v_mfma_f32_16x16x32_bf16 v[120:123], v[180:183], v[196:199], v[120:123]
	v_mfma_f32_16x16x32_bf16 v[108:111], v[172:175], v[204:207], v[108:111]
	v_mfma_f32_16x16x32_bf16 v[104:107], v[180:183], v[204:207], v[104:107]
	v_mfma_f32_16x16x32_bf16 v[68:71], v[172:175], v[228:231], v[68:71]
	v_mfma_f32_16x16x32_bf16 v[64:67], v[180:183], v[228:231], v[64:67]
	s_barrier
	ds_read_b128 v[184:187], v223 offset:16384
	ds_read_b128 v[188:191], v223 offset:17408
	ds_read_b128 v[192:195], v223 offset:18432
	ds_read_b128 v[196:199], v223 offset:19456
	ds_read_b128 v[200:203], v223 offset:20480
	ds_read_b128 v[204:207], v223 offset:21504
	ds_read_b128 v[224:227], v223 offset:22528
	ds_read_b128 v[228:231], v223 offset:23552
	s_mov_b32 m0, s55
	s_nop 0
	buffer_load_dwordx4 v220, s[48:51], s12 offen lds
	s_add_i32 s14, s12, 0x80000
	s_mov_b32 m0, s76
	s_nop 0
	buffer_load_dwordx4 v221, s[48:51], s12 offen lds
	s_nop 0
	s_mov_b32 m0, s77
	s_nop 0
	buffer_load_dwordx4 v220, s[48:51], s14 offen lds
	s_nop 0
	s_mov_b32 m0, s78
	s_nop 0
	buffer_load_dwordx4 v221, s[48:51], s14 offen lds
	s_nop 0
	s_mov_b32 m0, s31
	s_nop 0
	buffer_load_dwordx4 v220, s[64:67], s13 offen lds
	s_nop 0
	s_mov_b32 m0, s79
	s_nop 0
	buffer_load_dwordx4 v221, s[64:67], s13 offen lds
	s_waitcnt vmcnt(8)
	s_waitcnt lgkmcnt(0)
	s_barrier
	v_mfma_f32_16x16x32_bf16 v[60:63], v[128:131], v[184:187], v[60:63]
	v_mfma_f32_16x16x32_bf16 v[56:59], v[152:155], v[184:187], v[56:59]
	v_mfma_f32_16x16x32_bf16 v[44:47], v[128:131], v[192:195], v[44:47]
	v_mfma_f32_16x16x32_bf16 v[40:43], v[152:155], v[192:195], v[40:43]
	v_mfma_f32_16x16x32_bf16 v[28:31], v[128:131], v[200:203], v[28:31]
	v_mfma_f32_16x16x32_bf16 v[24:27], v[152:155], v[200:203], v[24:27]
	v_mfma_f32_16x16x32_bf16 v[12:15], v[128:131], v[224:227], v[12:15]
	v_mfma_f32_16x16x32_bf16 v[8:11], v[152:155], v[224:227], v[8:11]
	v_mfma_f32_16x16x32_bf16 v[60:63], v[140:143], v[188:191], v[60:63]
	v_mfma_f32_16x16x32_bf16 v[56:59], v[156:159], v[188:191], v[56:59]
	v_mfma_f32_16x16x32_bf16 v[44:47], v[140:143], v[196:199], v[44:47]
	v_mfma_f32_16x16x32_bf16 v[40:43], v[156:159], v[196:199], v[40:43]
	v_mfma_f32_16x16x32_bf16 v[28:31], v[140:143], v[204:207], v[28:31]
	v_mfma_f32_16x16x32_bf16 v[24:27], v[156:159], v[204:207], v[24:27]
	v_mfma_f32_16x16x32_bf16 v[12:15], v[140:143], v[228:231], v[12:15]
	v_mfma_f32_16x16x32_bf16 v[8:11], v[156:159], v[228:231], v[8:11]
	v_mfma_f32_16x16x32_bf16 v[52:55], v[168:171], v[184:187], v[52:55]
	v_mfma_f32_16x16x32_bf16 v[48:51], v[176:179], v[184:187], v[48:51]
	v_mfma_f32_16x16x32_bf16 v[36:39], v[168:171], v[192:195], v[36:39]
	v_mfma_f32_16x16x32_bf16 v[32:35], v[176:179], v[192:195], v[32:35]
	v_mfma_f32_16x16x32_bf16 v[20:23], v[168:171], v[200:203], v[20:23]
	v_mfma_f32_16x16x32_bf16 v[16:19], v[176:179], v[200:203], v[16:19]
	v_mfma_f32_16x16x32_bf16 v[4:7], v[168:171], v[224:227], v[4:7]
	v_mfma_f32_16x16x32_bf16 v[0:3], v[176:179], v[224:227], v[0:3]
	v_mfma_f32_16x16x32_bf16 v[52:55], v[172:175], v[188:191], v[52:55]
	v_mfma_f32_16x16x32_bf16 v[48:51], v[180:183], v[188:191], v[48:51]
	v_mfma_f32_16x16x32_bf16 v[36:39], v[172:175], v[196:199], v[36:39]
	v_mfma_f32_16x16x32_bf16 v[32:35], v[180:183], v[196:199], v[32:35]
	v_mfma_f32_16x16x32_bf16 v[20:23], v[172:175], v[204:207], v[20:23]
	v_mfma_f32_16x16x32_bf16 v[16:19], v[180:183], v[204:207], v[16:19]
	v_mfma_f32_16x16x32_bf16 v[4:7], v[172:175], v[228:231], v[4:7]
	v_mfma_f32_16x16x32_bf16 v[0:3], v[180:183], v[228:231], v[0:3]
	s_barrier
	v_add_u32_e32 v156, 0x18000, v222
	v_add_u32_e32 v180, 0x1c000, v222
	ds_read_b128 v[128:131], v156
	ds_read_b128 v[140:143], v156 offset:1024
	ds_read_b128 v[152:155], v156 offset:2048
	ds_read_b128 v[156:159], v156 offset:3072
	ds_read_b128 v[168:171], v180
	ds_read_b128 v[172:175], v180 offset:1024
	ds_read_b128 v[176:179], v180 offset:2048
	ds_read_b128 v[180:183], v180 offset:3072
	ds_read_b128 v[184:187], v223 offset:32768
	ds_read_b128 v[188:191], v223 offset:33792
	ds_read_b128 v[192:195], v223 offset:34816
	ds_read_b128 v[196:199], v223 offset:35840
	ds_read_b128 v[200:203], v223 offset:36864
	ds_read_b128 v[204:207], v223 offset:37888
	ds_read_b128 v[224:227], v223 offset:38912
	ds_read_b128 v[228:231], v223 offset:39936
	s_add_i32 s13, s13, 0x80000
	s_mov_b32 m0, s82
	s_nop 0
	buffer_load_dwordx4 v220, s[64:67], s13 offen lds
	s_nop 0
	s_mov_b32 m0, s83
	s_nop 0
	buffer_load_dwordx4 v221, s[64:67], s13 offen lds
	s_waitcnt vmcnt(8)
	s_waitcnt lgkmcnt(0)
	s_barrier
	v_mfma_f32_16x16x32_bf16 v[164:167], v[128:131], v[184:187], v[164:167]
	v_mfma_f32_16x16x32_bf16 v[160:163], v[152:155], v[184:187], v[160:163]
	v_mfma_f32_16x16x32_bf16 v[136:139], v[128:131], v[192:195], v[136:139]
	v_mfma_f32_16x16x32_bf16 v[132:135], v[152:155], v[192:195], v[132:135]
	v_mfma_f32_16x16x32_bf16 v[116:119], v[128:131], v[200:203], v[116:119]
	v_mfma_f32_16x16x32_bf16 v[112:115], v[152:155], v[200:203], v[112:115]
	v_mfma_f32_16x16x32_bf16 v[76:79], v[128:131], v[224:227], v[76:79]
	v_mfma_f32_16x16x32_bf16 v[72:75], v[152:155], v[224:227], v[72:75]
	v_mfma_f32_16x16x32_bf16 v[164:167], v[140:143], v[188:191], v[164:167]
	v_mfma_f32_16x16x32_bf16 v[160:163], v[156:159], v[188:191], v[160:163]
	v_mfma_f32_16x16x32_bf16 v[136:139], v[140:143], v[196:199], v[136:139]
	v_mfma_f32_16x16x32_bf16 v[132:135], v[156:159], v[196:199], v[132:135]
	v_mfma_f32_16x16x32_bf16 v[116:119], v[140:143], v[204:207], v[116:119]
	v_mfma_f32_16x16x32_bf16 v[112:115], v[156:159], v[204:207], v[112:115]
	v_mfma_f32_16x16x32_bf16 v[76:79], v[140:143], v[228:231], v[76:79]
	v_mfma_f32_16x16x32_bf16 v[72:75], v[156:159], v[228:231], v[72:75]
	v_mfma_f32_16x16x32_bf16 v[148:151], v[168:171], v[184:187], v[148:151]
	v_mfma_f32_16x16x32_bf16 v[144:147], v[176:179], v[184:187], v[144:147]
	v_mfma_f32_16x16x32_bf16 v[124:127], v[168:171], v[192:195], v[124:127]
	v_mfma_f32_16x16x32_bf16 v[120:123], v[176:179], v[192:195], v[120:123]
	v_mfma_f32_16x16x32_bf16 v[108:111], v[168:171], v[200:203], v[108:111]
	v_mfma_f32_16x16x32_bf16 v[104:107], v[176:179], v[200:203], v[104:107]
	v_mfma_f32_16x16x32_bf16 v[68:71], v[168:171], v[224:227], v[68:71]
	v_mfma_f32_16x16x32_bf16 v[64:67], v[176:179], v[224:227], v[64:67]
	v_mfma_f32_16x16x32_bf16 v[148:151], v[172:175], v[188:191], v[148:151]
	v_mfma_f32_16x16x32_bf16 v[144:147], v[180:183], v[188:191], v[144:147]
	v_mfma_f32_16x16x32_bf16 v[124:127], v[172:175], v[196:199], v[124:127]
	v_mfma_f32_16x16x32_bf16 v[120:123], v[180:183], v[196:199], v[120:123]
	v_mfma_f32_16x16x32_bf16 v[108:111], v[172:175], v[204:207], v[108:111]
	v_mfma_f32_16x16x32_bf16 v[104:107], v[180:183], v[204:207], v[104:107]
	v_mfma_f32_16x16x32_bf16 v[68:71], v[172:175], v[228:231], v[68:71]
	v_mfma_f32_16x16x32_bf16 v[64:67], v[180:183], v[228:231], v[64:67]
	s_barrier
	ds_read_b128 v[184:187], v223 offset:49152
	ds_read_b128 v[188:191], v223 offset:50176
	ds_read_b128 v[192:195], v223 offset:51200
	ds_read_b128 v[196:199], v223 offset:52224
	ds_read_b128 v[200:203], v223 offset:53248
	ds_read_b128 v[204:207], v223 offset:54272
	ds_read_b128 v[224:227], v223 offset:55296
	ds_read_b128 v[228:231], v223 offset:56320
	s_or_b32 s13, s12, 0x4000
	s_mov_b32 m0, s34
	s_nop 0
	buffer_load_dwordx4 v220, s[48:51], s13 offen lds
	s_add_i32 s12, s12, 0x84000
	s_mov_b32 m0, s84
	s_nop 0
	buffer_load_dwordx4 v221, s[48:51], s13 offen lds
	s_nop 0
	s_mov_b32 m0, s87
	s_nop 0
	buffer_load_dwordx4 v220, s[48:51], s12 offen lds
	s_nop 0
	s_mov_b32 m0, s88
	s_nop 0
	buffer_load_dwordx4 v221, s[48:51], s12 offen lds
	s_nop 0
	s_mov_b32 m0, s85
	s_nop 0
	buffer_load_dwordx4 v220, s[64:67], s11 offen lds
	s_nop 0
	s_mov_b32 m0, s86
	s_nop 0
	buffer_load_dwordx4 v221, s[64:67], s11 offen lds
	s_waitcnt vmcnt(8)
	s_waitcnt lgkmcnt(0)
	s_barrier
	v_mfma_f32_16x16x32_bf16 v[60:63], v[128:131], v[184:187], v[60:63]
	v_mfma_f32_16x16x32_bf16 v[56:59], v[152:155], v[184:187], v[56:59]
	v_mfma_f32_16x16x32_bf16 v[44:47], v[128:131], v[192:195], v[44:47]
	v_mfma_f32_16x16x32_bf16 v[40:43], v[152:155], v[192:195], v[40:43]
	v_mfma_f32_16x16x32_bf16 v[28:31], v[128:131], v[200:203], v[28:31]
	v_mfma_f32_16x16x32_bf16 v[24:27], v[152:155], v[200:203], v[24:27]
	v_mfma_f32_16x16x32_bf16 v[12:15], v[128:131], v[224:227], v[12:15]
	v_mfma_f32_16x16x32_bf16 v[8:11], v[152:155], v[224:227], v[8:11]
	v_mfma_f32_16x16x32_bf16 v[60:63], v[140:143], v[188:191], v[60:63]
	v_mfma_f32_16x16x32_bf16 v[56:59], v[156:159], v[188:191], v[56:59]
	v_mfma_f32_16x16x32_bf16 v[44:47], v[140:143], v[196:199], v[44:47]
	v_mfma_f32_16x16x32_bf16 v[40:43], v[156:159], v[196:199], v[40:43]
	v_mfma_f32_16x16x32_bf16 v[28:31], v[140:143], v[204:207], v[28:31]
	v_mfma_f32_16x16x32_bf16 v[24:27], v[156:159], v[204:207], v[24:27]
	v_mfma_f32_16x16x32_bf16 v[12:15], v[140:143], v[228:231], v[12:15]
	v_mfma_f32_16x16x32_bf16 v[8:11], v[156:159], v[228:231], v[8:11]
	v_mfma_f32_16x16x32_bf16 v[52:55], v[168:171], v[184:187], v[52:55]
	v_mfma_f32_16x16x32_bf16 v[48:51], v[176:179], v[184:187], v[48:51]
	v_mfma_f32_16x16x32_bf16 v[36:39], v[168:171], v[192:195], v[36:39]
	v_mfma_f32_16x16x32_bf16 v[32:35], v[176:179], v[192:195], v[32:35]
	v_mfma_f32_16x16x32_bf16 v[20:23], v[168:171], v[200:203], v[20:23]
	v_mfma_f32_16x16x32_bf16 v[16:19], v[176:179], v[200:203], v[16:19]
	v_mfma_f32_16x16x32_bf16 v[4:7], v[168:171], v[224:227], v[4:7]
	v_mfma_f32_16x16x32_bf16 v[0:3], v[176:179], v[224:227], v[0:3]
	v_mfma_f32_16x16x32_bf16 v[52:55], v[172:175], v[188:191], v[52:55]
	v_mfma_f32_16x16x32_bf16 v[48:51], v[180:183], v[188:191], v[48:51]
	v_mfma_f32_16x16x32_bf16 v[36:39], v[172:175], v[196:199], v[36:39]
	v_mfma_f32_16x16x32_bf16 v[32:35], v[180:183], v[196:199], v[32:35]
	v_mfma_f32_16x16x32_bf16 v[20:23], v[172:175], v[204:207], v[20:23]
	v_mfma_f32_16x16x32_bf16 v[16:19], v[180:183], v[204:207], v[16:19]
	v_mfma_f32_16x16x32_bf16 v[4:7], v[172:175], v[228:231], v[4:7]
	v_mfma_f32_16x16x32_bf16 v[0:3], v[180:183], v[228:231], v[0:3]
	s_barrier
	s_add_i32 s10, s10, 2
	s_add_i32 s8, s8, 0x8000
	s_add_i32 s9, s9, 0x8000
	s_cmp_gt_u32 s10, 29
	s_cbranch_scc0 .LBB0_691

.Lnb_p5:
	s_add_i32 s53, s37, 0xfff84000
	s_cmp_eq_u32 s52, 28
	s_cselect_b32 s56, s4, s53
	s_cselect_b32 s55, s5, s51
	s_or_b32 s53, s56, 0x4000
	s_mov_b32 m0, s41
	s_nop 0
	buffer_load_dwordx4 v166, s[24:27], s37 offen lds
	s_nop 0
	s_mov_b32 m0, s42
	s_nop 0
	buffer_load_dwordx4 v167, s[24:27], s37 offen lds
	s_waitcnt vmcnt(24)
	s_waitcnt lgkmcnt(0)
	s_barrier
	v_mfma_f32_16x16x32_bf16 v[148:151], v[152:155], v[190:193], 0
	v_mfma_f32_16x16x32_bf16 v[140:143], v[160:163], v[190:193], 0
	v_mfma_f32_16x16x32_bf16 v[132:135], v[152:155], v[198:201], 0
	v_mfma_f32_16x16x32_bf16 v[124:127], v[160:163], v[198:201], 0
	v_mfma_f32_16x16x32_bf16 v[116:119], v[152:155], v[220:223], 0
	v_mfma_f32_16x16x32_bf16 v[108:111], v[160:163], v[220:223], 0
	v_mfma_f32_16x16x32_bf16 v[76:79], v[152:155], v[228:231], 0
	v_mfma_f32_16x16x32_bf16 v[68:71], v[160:163], v[228:231], 0
	v_mfma_f32_16x16x32_bf16 v[148:151], v[156:159], v[194:197], v[148:151]
	v_mfma_f32_16x16x32_bf16 v[140:143], v[170:173], v[194:197], v[140:143]
	v_mfma_f32_16x16x32_bf16 v[132:135], v[156:159], v[202:205], v[132:135]
	v_mfma_f32_16x16x32_bf16 v[124:127], v[170:173], v[202:205], v[124:127]
	v_mfma_f32_16x16x32_bf16 v[116:119], v[156:159], v[224:227], v[116:119]
	v_mfma_f32_16x16x32_bf16 v[108:111], v[170:173], v[224:227], v[108:111]
	v_mfma_f32_16x16x32_bf16 v[76:79], v[156:159], v[240:243], v[76:79]
	v_mfma_f32_16x16x32_bf16 v[68:71], v[170:173], v[240:243], v[68:71]
	v_mfma_f32_16x16x32_bf16 v[144:147], v[174:177], v[190:193], 0
	v_mfma_f32_16x16x32_bf16 v[136:139], v[182:185], v[190:193], 0
	v_mfma_f32_16x16x32_bf16 v[128:131], v[174:177], v[198:201], 0
	v_mfma_f32_16x16x32_bf16 v[120:123], v[182:185], v[198:201], 0
	v_mfma_f32_16x16x32_bf16 v[112:115], v[174:177], v[220:223], 0
	v_mfma_f32_16x16x32_bf16 v[104:107], v[182:185], v[220:223], 0
	v_mfma_f32_16x16x32_bf16 v[72:75], v[174:177], v[228:231], 0
	v_mfma_f32_16x16x32_bf16 v[64:67], v[182:185], v[228:231], 0
	v_mfma_f32_16x16x32_bf16 v[144:147], v[178:181], v[194:197], v[144:147]
	v_mfma_f32_16x16x32_bf16 v[136:139], v[186:189], v[194:197], v[136:139]
	v_mfma_f32_16x16x32_bf16 v[128:131], v[178:181], v[202:205], v[128:131]
	v_mfma_f32_16x16x32_bf16 v[120:123], v[186:189], v[202:205], v[120:123]
	v_mfma_f32_16x16x32_bf16 v[112:115], v[178:181], v[224:227], v[112:115]
	v_mfma_f32_16x16x32_bf16 v[104:107], v[186:189], v[224:227], v[104:107]
	v_mfma_f32_16x16x32_bf16 v[72:75], v[178:181], v[240:243], v[72:75]
	v_mfma_f32_16x16x32_bf16 v[64:67], v[186:189], v[240:243], v[64:67]
	s_barrier
	ds_read_b128 v[190:193], v169 offset:16384
	ds_read_b128 v[194:197], v169 offset:17408
	ds_read_b128 v[198:201], v169 offset:18432
	ds_read_b128 v[202:205], v169 offset:19456
	ds_read_b128 v[220:223], v169 offset:20480
	ds_read_b128 v[224:227], v169 offset:21504
	ds_read_b128 v[228:231], v169 offset:22528
	ds_read_b128 v[240:243], v169 offset:23552
	s_mov_b32 m0, s7
	s_nop 0
	buffer_load_dwordx4 v166, s[28:31], s55 offen lds
	s_add_i32 s57, s55, 0x80000
	s_mov_b32 m0, s8
	s_nop 0
	buffer_load_dwordx4 v167, s[28:31], s55 offen lds
	s_nop 0
	s_mov_b32 m0, s9
	s_nop 0
	buffer_load_dwordx4 v166, s[28:31], s57 offen lds
	s_nop 0
	s_mov_b32 m0, s10
	s_nop 0
	buffer_load_dwordx4 v167, s[28:31], s57 offen lds
	s_nop 0
	s_mov_b32 m0, s6
	s_nop 0
	buffer_load_dwordx4 v166, s[24:27], s56 offen lds
	s_nop 0
	s_mov_b32 m0, s11
	s_nop 0
	buffer_load_dwordx4 v167, s[24:27], s56 offen lds
	s_waitcnt vmcnt(24)
	s_waitcnt lgkmcnt(0)
	s_barrier
	v_mfma_f32_16x16x32_bf16 v[60:63], v[152:155], v[190:193], 0
	v_mfma_f32_16x16x32_bf16 v[52:55], v[160:163], v[190:193], 0
	v_mfma_f32_16x16x32_bf16 v[44:47], v[152:155], v[198:201], 0
	v_mfma_f32_16x16x32_bf16 v[36:39], v[160:163], v[198:201], 0
	v_mfma_f32_16x16x32_bf16 v[28:31], v[152:155], v[220:223], 0
	v_mfma_f32_16x16x32_bf16 v[20:23], v[160:163], v[220:223], 0
	v_mfma_f32_16x16x32_bf16 v[12:15], v[152:155], v[228:231], 0
	v_mfma_f32_16x16x32_bf16 v[4:7], v[160:163], v[228:231], 0
	v_mfma_f32_16x16x32_bf16 v[60:63], v[156:159], v[194:197], v[60:63]
	v_mfma_f32_16x16x32_bf16 v[52:55], v[170:173], v[194:197], v[52:55]
	v_mfma_f32_16x16x32_bf16 v[44:47], v[156:159], v[202:205], v[44:47]
	v_mfma_f32_16x16x32_bf16 v[36:39], v[170:173], v[202:205], v[36:39]
	v_mfma_f32_16x16x32_bf16 v[28:31], v[156:159], v[224:227], v[28:31]
	v_mfma_f32_16x16x32_bf16 v[20:23], v[170:173], v[224:227], v[20:23]
	v_mfma_f32_16x16x32_bf16 v[12:15], v[156:159], v[240:243], v[12:15]
	v_mfma_f32_16x16x32_bf16 v[4:7], v[170:173], v[240:243], v[4:7]
	v_mfma_f32_16x16x32_bf16 v[56:59], v[174:177], v[190:193], 0
	v_mfma_f32_16x16x32_bf16 v[48:51], v[182:185], v[190:193], 0
	v_mfma_f32_16x16x32_bf16 v[40:43], v[174:177], v[198:201], 0
	v_mfma_f32_16x16x32_bf16 v[32:35], v[182:185], v[198:201], 0
	v_mfma_f32_16x16x32_bf16 v[24:27], v[174:177], v[220:223], 0
	v_mfma_f32_16x16x32_bf16 v[16:19], v[182:185], v[220:223], 0
	v_mfma_f32_16x16x32_bf16 v[8:11], v[174:177], v[228:231], 0
	v_mfma_f32_16x16x32_bf16 v[0:3], v[182:185], v[228:231], 0
	v_mfma_f32_16x16x32_bf16 v[56:59], v[178:181], v[194:197], v[56:59]
	v_mfma_f32_16x16x32_bf16 v[48:51], v[186:189], v[194:197], v[48:51]
	v_mfma_f32_16x16x32_bf16 v[40:43], v[178:181], v[202:205], v[40:43]
	v_mfma_f32_16x16x32_bf16 v[32:35], v[186:189], v[202:205], v[32:35]
	v_mfma_f32_16x16x32_bf16 v[24:27], v[178:181], v[224:227], v[24:27]
	v_mfma_f32_16x16x32_bf16 v[16:19], v[186:189], v[224:227], v[16:19]
	v_mfma_f32_16x16x32_bf16 v[8:11], v[178:181], v[240:243], v[8:11]
	v_mfma_f32_16x16x32_bf16 v[0:3], v[186:189], v[240:243], v[0:3]
	s_barrier
	v_add_u32_e32 v164, 0x18000, v168
	ds_read_b128 v[152:155], v164
	ds_read_b128 v[156:159], v164 offset:1024
	ds_read_b128 v[160:163], v164 offset:2048
	ds_read_b128 v[170:173], v164 offset:3072
	v_add_u32_e32 v164, 0x1c000, v168
	ds_read_b128 v[174:177], v164
	ds_read_b128 v[178:181], v164 offset:1024
	ds_read_b128 v[182:185], v164 offset:2048
	ds_read_b128 v[186:189], v164 offset:3072
	ds_read_b128 v[190:193], v169 offset:32768
	ds_read_b128 v[194:197], v169 offset:33792
	ds_read_b128 v[198:201], v169 offset:34816
	ds_read_b128 v[202:205], v169 offset:35840
	ds_read_b128 v[220:223], v169 offset:36864
	ds_read_b128 v[224:227], v169 offset:37888
	ds_read_b128 v[228:231], v169 offset:38912
	ds_read_b128 v[240:243], v169 offset:39936
	s_add_i32 s56, s56, 0x80000
	s_mov_b32 m0, s12
	s_nop 0
	buffer_load_dwordx4 v166, s[24:27], s56 offen lds
	s_nop 0
	s_mov_b32 m0, s13
	s_nop 0
	buffer_load_dwordx4 v167, s[24:27], s56 offen lds
	s_waitcnt vmcnt(8)
	s_waitcnt lgkmcnt(0)
	s_barrier
	v_mfma_f32_16x16x32_bf16 v[148:151], v[152:155], v[190:193], v[148:151]
	v_mfma_f32_16x16x32_bf16 v[140:143], v[160:163], v[190:193], v[140:143]
	v_mfma_f32_16x16x32_bf16 v[132:135], v[152:155], v[198:201], v[132:135]
	v_mfma_f32_16x16x32_bf16 v[124:127], v[160:163], v[198:201], v[124:127]
	v_mfma_f32_16x16x32_bf16 v[116:119], v[152:155], v[220:223], v[116:119]
	v_mfma_f32_16x16x32_bf16 v[108:111], v[160:163], v[220:223], v[108:111]
	v_mfma_f32_16x16x32_bf16 v[76:79], v[152:155], v[228:231], v[76:79]
	v_mfma_f32_16x16x32_bf16 v[68:71], v[160:163], v[228:231], v[68:71]
	v_mfma_f32_16x16x32_bf16 v[148:151], v[156:159], v[194:197], v[148:151]
	v_mfma_f32_16x16x32_bf16 v[140:143], v[170:173], v[194:197], v[140:143]
	v_mfma_f32_16x16x32_bf16 v[132:135], v[156:159], v[202:205], v[132:135]
	v_mfma_f32_16x16x32_bf16 v[124:127], v[170:173], v[202:205], v[124:127]
	v_mfma_f32_16x16x32_bf16 v[116:119], v[156:159], v[224:227], v[116:119]
	v_mfma_f32_16x16x32_bf16 v[108:111], v[170:173], v[224:227], v[108:111]
	v_mfma_f32_16x16x32_bf16 v[76:79], v[156:159], v[240:243], v[76:79]
	v_mfma_f32_16x16x32_bf16 v[68:71], v[170:173], v[240:243], v[68:71]
	v_mfma_f32_16x16x32_bf16 v[144:147], v[174:177], v[190:193], v[144:147]
	v_mfma_f32_16x16x32_bf16 v[136:139], v[182:185], v[190:193], v[136:139]
	v_mfma_f32_16x16x32_bf16 v[128:131], v[174:177], v[198:201], v[128:131]
	v_mfma_f32_16x16x32_bf16 v[120:123], v[182:185], v[198:201], v[120:123]
	v_mfma_f32_16x16x32_bf16 v[112:115], v[174:177], v[220:223], v[112:115]
	v_mfma_f32_16x16x32_bf16 v[104:107], v[182:185], v[220:223], v[104:107]
	v_mfma_f32_16x16x32_bf16 v[72:75], v[174:177], v[228:231], v[72:75]
	v_mfma_f32_16x16x32_bf16 v[64:67], v[182:185], v[228:231], v[64:67]
	v_mfma_f32_16x16x32_bf16 v[144:147], v[178:181], v[194:197], v[144:147]
	v_mfma_f32_16x16x32_bf16 v[136:139], v[186:189], v[194:197], v[136:139]
	v_mfma_f32_16x16x32_bf16 v[128:131], v[178:181], v[202:205], v[128:131]
	v_mfma_f32_16x16x32_bf16 v[120:123], v[186:189], v[202:205], v[120:123]
	v_mfma_f32_16x16x32_bf16 v[112:115], v[178:181], v[224:227], v[112:115]
	v_mfma_f32_16x16x32_bf16 v[104:107], v[186:189], v[224:227], v[104:107]
	v_mfma_f32_16x16x32_bf16 v[72:75], v[178:181], v[240:243], v[72:75]
	v_mfma_f32_16x16x32_bf16 v[64:67], v[186:189], v[240:243], v[64:67]
	s_barrier
	ds_read_b128 v[190:193], v169 offset:49152
	ds_read_b128 v[194:197], v169 offset:50176
	ds_read_b128 v[198:201], v169 offset:51200
	ds_read_b128 v[202:205], v169 offset:52224
	ds_read_b128 v[220:223], v169 offset:53248
	ds_read_b128 v[224:227], v169 offset:54272
	ds_read_b128 v[228:231], v169 offset:55296
	ds_read_b128 v[240:243], v169 offset:56320
	s_or_b32 s56, s55, 0x4000
	s_mov_b32 m0, s16
	s_nop 0
	buffer_load_dwordx4 v166, s[28:31], s56 offen lds
	s_add_i32 s55, s55, 0x84000
	s_mov_b32 m0, s17
	s_nop 0
	buffer_load_dwordx4 v167, s[28:31], s56 offen lds
	s_nop 0
	s_mov_b32 m0, s34
	s_nop 0
	buffer_load_dwordx4 v166, s[28:31], s55 offen lds
	s_nop 0
	s_mov_b32 m0, s40
	s_nop 0
	buffer_load_dwordx4 v167, s[28:31], s55 offen lds
	s_nop 0
	s_mov_b32 m0, s18
	s_nop 0
	buffer_load_dwordx4 v166, s[24:27], s53 offen lds
	s_nop 0
	s_mov_b32 m0, s19
	s_nop 0
	buffer_load_dwordx4 v167, s[24:27], s53 offen lds
	s_waitcnt vmcnt(8)
	s_waitcnt lgkmcnt(0)
	s_barrier
	v_mfma_f32_16x16x32_bf16 v[60:63], v[152:155], v[190:193], v[60:63]
	v_mfma_f32_16x16x32_bf16 v[52:55], v[160:163], v[190:193], v[52:55]
	v_mfma_f32_16x16x32_bf16 v[44:47], v[152:155], v[198:201], v[44:47]
	v_mfma_f32_16x16x32_bf16 v[36:39], v[160:163], v[198:201], v[36:39]
	v_mfma_f32_16x16x32_bf16 v[28:31], v[152:155], v[220:223], v[28:31]
	v_mfma_f32_16x16x32_bf16 v[20:23], v[160:163], v[220:223], v[20:23]
	v_mfma_f32_16x16x32_bf16 v[12:15], v[152:155], v[228:231], v[12:15]
	v_mfma_f32_16x16x32_bf16 v[4:7], v[160:163], v[228:231], v[4:7]
	v_mfma_f32_16x16x32_bf16 v[60:63], v[156:159], v[194:197], v[60:63]
	v_mfma_f32_16x16x32_bf16 v[52:55], v[170:173], v[194:197], v[52:55]
	v_mfma_f32_16x16x32_bf16 v[44:47], v[156:159], v[202:205], v[44:47]
	v_mfma_f32_16x16x32_bf16 v[36:39], v[170:173], v[202:205], v[36:39]
	v_mfma_f32_16x16x32_bf16 v[28:31], v[156:159], v[224:227], v[28:31]
	v_mfma_f32_16x16x32_bf16 v[20:23], v[170:173], v[224:227], v[20:23]
	v_mfma_f32_16x16x32_bf16 v[12:15], v[156:159], v[240:243], v[12:15]
	v_mfma_f32_16x16x32_bf16 v[4:7], v[170:173], v[240:243], v[4:7]
	v_mfma_f32_16x16x32_bf16 v[56:59], v[174:177], v[190:193], v[56:59]
	v_mfma_f32_16x16x32_bf16 v[48:51], v[182:185], v[190:193], v[48:51]
	v_mfma_f32_16x16x32_bf16 v[40:43], v[174:177], v[198:201], v[40:43]
	v_mfma_f32_16x16x32_bf16 v[32:35], v[182:185], v[198:201], v[32:35]
	v_mfma_f32_16x16x32_bf16 v[24:27], v[174:177], v[220:223], v[24:27]
	v_mfma_f32_16x16x32_bf16 v[16:19], v[182:185], v[220:223], v[16:19]
	v_mfma_f32_16x16x32_bf16 v[8:11], v[174:177], v[228:231], v[8:11]
	v_mfma_f32_16x16x32_bf16 v[0:3], v[182:185], v[228:231], v[0:3]
	v_mfma_f32_16x16x32_bf16 v[56:59], v[178:181], v[194:197], v[56:59]
	v_mfma_f32_16x16x32_bf16 v[48:51], v[186:189], v[194:197], v[48:51]
	v_mfma_f32_16x16x32_bf16 v[40:43], v[178:181], v[202:205], v[40:43]
	v_mfma_f32_16x16x32_bf16 v[32:35], v[186:189], v[202:205], v[32:35]
	v_mfma_f32_16x16x32_bf16 v[24:27], v[178:181], v[224:227], v[24:27]
	v_mfma_f32_16x16x32_bf16 v[16:19], v[186:189], v[224:227], v[16:19]
	v_mfma_f32_16x16x32_bf16 v[8:11], v[178:181], v[240:243], v[8:11]
	v_mfma_f32_16x16x32_bf16 v[0:3], v[186:189], v[240:243], v[0:3]
	s_barrier
	s_add_i32 s52, s52, 2
	s_add_i32 s37, s37, 0x8000
	s_add_i32 s51, s51, 0x8000
.LBB0_795:
	v_add_u32_e32 v164, 0x10000, v168
	ds_read_b128 v[152:155], v164
	ds_read_b128 v[156:159], v164 offset:1024
	ds_read_b128 v[160:163], v164 offset:2048
	ds_read_b128 v[170:173], v164 offset:3072
	v_add_u32_e32 v164, 0x14000, v168
	ds_read_b128 v[174:177], v164
	ds_read_b128 v[178:181], v164 offset:1024
	ds_read_b128 v[182:185], v164 offset:2048
	ds_read_b128 v[186:189], v164 offset:3072
	s_add_i32 s53, s37, 0xfff84000
	s_cmp_eq_u32 s52, 28
	s_cselect_b32 s56, s4, s53
	s_cselect_b32 s55, s5, s51
	s_or_b32 s53, s56, 0x4000
	ds_read_b128 v[190:193], v169
	ds_read_b128 v[194:197], v169 offset:1024
	ds_read_b128 v[198:201], v169 offset:2048
	ds_read_b128 v[202:205], v169 offset:3072
	ds_read_b128 v[220:223], v169 offset:4096
	ds_read_b128 v[224:227], v169 offset:5120
	ds_read_b128 v[228:231], v169 offset:6144
	ds_read_b128 v[240:243], v169 offset:7168
	s_mov_b32 m0, s41
	s_nop 0
	buffer_load_dwordx4 v166, s[24:27], s37 offen lds
	s_nop 0
	s_mov_b32 m0, s42
	s_nop 0
	buffer_load_dwordx4 v167, s[24:27], s37 offen lds
	s_waitcnt vmcnt(8)
	s_waitcnt lgkmcnt(0)
	s_barrier
	v_mfma_f32_16x16x32_bf16 v[148:151], v[152:155], v[190:193], v[148:151]
	v_mfma_f32_16x16x32_bf16 v[140:143], v[160:163], v[190:193], v[140:143]
	v_mfma_f32_16x16x32_bf16 v[132:135], v[152:155], v[198:201], v[132:135]
	v_mfma_f32_16x16x32_bf16 v[124:127], v[160:163], v[198:201], v[124:127]
	v_mfma_f32_16x16x32_bf16 v[116:119], v[152:155], v[220:223], v[116:119]
	v_mfma_f32_16x16x32_bf16 v[108:111], v[160:163], v[220:223], v[108:111]
	v_mfma_f32_16x16x32_bf16 v[76:79], v[152:155], v[228:231], v[76:79]
	v_mfma_f32_16x16x32_bf16 v[68:71], v[160:163], v[228:231], v[68:71]
	v_mfma_f32_16x16x32_bf16 v[148:151], v[156:159], v[194:197], v[148:151]
	v_mfma_f32_16x16x32_bf16 v[140:143], v[170:173], v[194:197], v[140:143]
	v_mfma_f32_16x16x32_bf16 v[132:135], v[156:159], v[202:205], v[132:135]
	v_mfma_f32_16x16x32_bf16 v[124:127], v[170:173], v[202:205], v[124:127]
	v_mfma_f32_16x16x32_bf16 v[116:119], v[156:159], v[224:227], v[116:119]
	v_mfma_f32_16x16x32_bf16 v[108:111], v[170:173], v[224:227], v[108:111]
	v_mfma_f32_16x16x32_bf16 v[76:79], v[156:159], v[240:243], v[76:79]
	v_mfma_f32_16x16x32_bf16 v[68:71], v[170:173], v[240:243], v[68:71]
	v_mfma_f32_16x16x32_bf16 v[144:147], v[174:177], v[190:193], v[144:147]
	v_mfma_f32_16x16x32_bf16 v[136:139], v[182:185], v[190:193], v[136:139]
	v_mfma_f32_16x16x32_bf16 v[128:131], v[174:177], v[198:201], v[128:131]
	v_mfma_f32_16x16x32_bf16 v[120:123], v[182:185], v[198:201], v[120:123]
	v_mfma_f32_16x16x32_bf16 v[112:115], v[174:177], v[220:223], v[112:115]
	v_mfma_f32_16x16x32_bf16 v[104:107], v[182:185], v[220:223], v[104:107]
	v_mfma_f32_16x16x32_bf16 v[72:75], v[174:177], v[228:231], v[72:75]
	v_mfma_f32_16x16x32_bf16 v[64:67], v[182:185], v[228:231], v[64:67]
	v_mfma_f32_16x16x32_bf16 v[144:147], v[178:181], v[194:197], v[144:147]
	v_mfma_f32_16x16x32_bf16 v[136:139], v[186:189], v[194:197], v[136:139]
	v_mfma_f32_16x16x32_bf16 v[128:131], v[178:181], v[202:205], v[128:131]
	v_mfma_f32_16x16x32_bf16 v[120:123], v[186:189], v[202:205], v[120:123]
	v_mfma_f32_16x16x32_bf16 v[112:115], v[178:181], v[224:227], v[112:115]
	v_mfma_f32_16x16x32_bf16 v[104:107], v[186:189], v[224:227], v[104:107]
	v_mfma_f32_16x16x32_bf16 v[72:75], v[178:181], v[240:243], v[72:75]
	v_mfma_f32_16x16x32_bf16 v[64:67], v[186:189], v[240:243], v[64:67]
	s_barrier
	ds_read_b128 v[190:193], v169 offset:16384
	ds_read_b128 v[194:197], v169 offset:17408
	ds_read_b128 v[198:201], v169 offset:18432
	ds_read_b128 v[202:205], v169 offset:19456
	ds_read_b128 v[220:223], v169 offset:20480
	ds_read_b128 v[224:227], v169 offset:21504
	ds_read_b128 v[228:231], v169 offset:22528
	ds_read_b128 v[240:243], v169 offset:23552
	s_mov_b32 m0, s7
	s_nop 0
	buffer_load_dwordx4 v166, s[28:31], s55 offen lds
	s_add_i32 s57, s55, 0x80000
	s_mov_b32 m0, s8
	s_nop 0
	buffer_load_dwordx4 v167, s[28:31], s55 offen lds
	s_nop 0
	s_mov_b32 m0, s9
	s_nop 0
	buffer_load_dwordx4 v166, s[28:31], s57 offen lds
	s_nop 0
	s_mov_b32 m0, s10
	s_nop 0
	buffer_load_dwordx4 v167, s[28:31], s57 offen lds
	s_nop 0
	s_mov_b32 m0, s6
	s_nop 0
	buffer_load_dwordx4 v166, s[24:27], s56 offen lds
	s_nop 0
	s_mov_b32 m0, s11
	s_nop 0
	buffer_load_dwordx4 v167, s[24:27], s56 offen lds
	s_waitcnt vmcnt(8)
	s_waitcnt lgkmcnt(0)
	s_barrier
	v_mfma_f32_16x16x32_bf16 v[60:63], v[152:155], v[190:193], v[60:63]
	v_mfma_f32_16x16x32_bf16 v[52:55], v[160:163], v[190:193], v[52:55]
	v_mfma_f32_16x16x32_bf16 v[44:47], v[152:155], v[198:201], v[44:47]
	v_mfma_f32_16x16x32_bf16 v[36:39], v[160:163], v[198:201], v[36:39]
	v_mfma_f32_16x16x32_bf16 v[28:31], v[152:155], v[220:223], v[28:31]
	v_mfma_f32_16x16x32_bf16 v[20:23], v[160:163], v[220:223], v[20:23]
	v_mfma_f32_16x16x32_bf16 v[12:15], v[152:155], v[228:231], v[12:15]
	v_mfma_f32_16x16x32_bf16 v[4:7], v[160:163], v[228:231], v[4:7]
	v_mfma_f32_16x16x32_bf16 v[60:63], v[156:159], v[194:197], v[60:63]
	v_mfma_f32_16x16x32_bf16 v[52:55], v[170:173], v[194:197], v[52:55]
	v_mfma_f32_16x16x32_bf16 v[44:47], v[156:159], v[202:205], v[44:47]
	v_mfma_f32_16x16x32_bf16 v[36:39], v[170:173], v[202:205], v[36:39]
	v_mfma_f32_16x16x32_bf16 v[28:31], v[156:159], v[224:227], v[28:31]
	v_mfma_f32_16x16x32_bf16 v[20:23], v[170:173], v[224:227], v[20:23]
	v_mfma_f32_16x16x32_bf16 v[12:15], v[156:159], v[240:243], v[12:15]
	v_mfma_f32_16x16x32_bf16 v[4:7], v[170:173], v[240:243], v[4:7]
	v_mfma_f32_16x16x32_bf16 v[56:59], v[174:177], v[190:193], v[56:59]
	v_mfma_f32_16x16x32_bf16 v[48:51], v[182:185], v[190:193], v[48:51]
	v_mfma_f32_16x16x32_bf16 v[40:43], v[174:177], v[198:201], v[40:43]
	v_mfma_f32_16x16x32_bf16 v[32:35], v[182:185], v[198:201], v[32:35]
	v_mfma_f32_16x16x32_bf16 v[24:27], v[174:177], v[220:223], v[24:27]
	v_mfma_f32_16x16x32_bf16 v[16:19], v[182:185], v[220:223], v[16:19]
	v_mfma_f32_16x16x32_bf16 v[8:11], v[174:177], v[228:231], v[8:11]
	v_mfma_f32_16x16x32_bf16 v[0:3], v[182:185], v[228:231], v[0:3]
	v_mfma_f32_16x16x32_bf16 v[56:59], v[178:181], v[194:197], v[56:59]
	v_mfma_f32_16x16x32_bf16 v[48:51], v[186:189], v[194:197], v[48:51]
	v_mfma_f32_16x16x32_bf16 v[40:43], v[178:181], v[202:205], v[40:43]
	v_mfma_f32_16x16x32_bf16 v[32:35], v[186:189], v[202:205], v[32:35]
	v_mfma_f32_16x16x32_bf16 v[24:27], v[178:181], v[224:227], v[24:27]
	v_mfma_f32_16x16x32_bf16 v[16:19], v[186:189], v[224:227], v[16:19]
	v_mfma_f32_16x16x32_bf16 v[8:11], v[178:181], v[240:243], v[8:11]
	v_mfma_f32_16x16x32_bf16 v[0:3], v[186:189], v[240:243], v[0:3]
	s_barrier
	v_add_u32_e32 v164, 0x18000, v168
	ds_read_b128 v[152:155], v164
	ds_read_b128 v[156:159], v164 offset:1024
	ds_read_b128 v[160:163], v164 offset:2048
	ds_read_b128 v[170:173], v164 offset:3072
	v_add_u32_e32 v164, 0x1c000, v168
	ds_read_b128 v[174:177], v164
	ds_read_b128 v[178:181], v164 offset:1024
	ds_read_b128 v[182:185], v164 offset:2048
	ds_read_b128 v[186:189], v164 offset:3072
	ds_read_b128 v[190:193], v169 offset:32768
	ds_read_b128 v[194:197], v169 offset:33792
	ds_read_b128 v[198:201], v169 offset:34816
	ds_read_b128 v[202:205], v169 offset:35840
	ds_read_b128 v[220:223], v169 offset:36864
	ds_read_b128 v[224:227], v169 offset:37888
	ds_read_b128 v[228:231], v169 offset:38912
	ds_read_b128 v[240:243], v169 offset:39936
	s_add_i32 s56, s56, 0x80000
	s_mov_b32 m0, s12
	s_nop 0
	buffer_load_dwordx4 v166, s[24:27], s56 offen lds
	s_nop 0
	s_mov_b32 m0, s13
	s_nop 0
	buffer_load_dwordx4 v167, s[24:27], s56 offen lds
	s_waitcnt vmcnt(8)
	s_waitcnt lgkmcnt(0)
	s_barrier
	v_mfma_f32_16x16x32_bf16 v[148:151], v[152:155], v[190:193], v[148:151]
	v_mfma_f32_16x16x32_bf16 v[140:143], v[160:163], v[190:193], v[140:143]
	v_mfma_f32_16x16x32_bf16 v[132:135], v[152:155], v[198:201], v[132:135]
	v_mfma_f32_16x16x32_bf16 v[124:127], v[160:163], v[198:201], v[124:127]
	v_mfma_f32_16x16x32_bf16 v[116:119], v[152:155], v[220:223], v[116:119]
	v_mfma_f32_16x16x32_bf16 v[108:111], v[160:163], v[220:223], v[108:111]
	v_mfma_f32_16x16x32_bf16 v[76:79], v[152:155], v[228:231], v[76:79]
	v_mfma_f32_16x16x32_bf16 v[68:71], v[160:163], v[228:231], v[68:71]
	v_mfma_f32_16x16x32_bf16 v[148:151], v[156:159], v[194:197], v[148:151]
	v_mfma_f32_16x16x32_bf16 v[140:143], v[170:173], v[194:197], v[140:143]
	v_mfma_f32_16x16x32_bf16 v[132:135], v[156:159], v[202:205], v[132:135]
	v_mfma_f32_16x16x32_bf16 v[124:127], v[170:173], v[202:205], v[124:127]
	v_mfma_f32_16x16x32_bf16 v[116:119], v[156:159], v[224:227], v[116:119]
	v_mfma_f32_16x16x32_bf16 v[108:111], v[170:173], v[224:227], v[108:111]
	v_mfma_f32_16x16x32_bf16 v[76:79], v[156:159], v[240:243], v[76:79]
	v_mfma_f32_16x16x32_bf16 v[68:71], v[170:173], v[240:243], v[68:71]
	v_mfma_f32_16x16x32_bf16 v[144:147], v[174:177], v[190:193], v[144:147]
	v_mfma_f32_16x16x32_bf16 v[136:139], v[182:185], v[190:193], v[136:139]
	v_mfma_f32_16x16x32_bf16 v[128:131], v[174:177], v[198:201], v[128:131]
	v_mfma_f32_16x16x32_bf16 v[120:123], v[182:185], v[198:201], v[120:123]
	v_mfma_f32_16x16x32_bf16 v[112:115], v[174:177], v[220:223], v[112:115]
	v_mfma_f32_16x16x32_bf16 v[104:107], v[182:185], v[220:223], v[104:107]
	v_mfma_f32_16x16x32_bf16 v[72:75], v[174:177], v[228:231], v[72:75]
	v_mfma_f32_16x16x32_bf16 v[64:67], v[182:185], v[228:231], v[64:67]
	v_mfma_f32_16x16x32_bf16 v[144:147], v[178:181], v[194:197], v[144:147]
	v_mfma_f32_16x16x32_bf16 v[136:139], v[186:189], v[194:197], v[136:139]
	v_mfma_f32_16x16x32_bf16 v[128:131], v[178:181], v[202:205], v[128:131]
	v_mfma_f32_16x16x32_bf16 v[120:123], v[186:189], v[202:205], v[120:123]
	v_mfma_f32_16x16x32_bf16 v[112:115], v[178:181], v[224:227], v[112:115]
	v_mfma_f32_16x16x32_bf16 v[104:107], v[186:189], v[224:227], v[104:107]
	v_mfma_f32_16x16x32_bf16 v[72:75], v[178:181], v[240:243], v[72:75]
	v_mfma_f32_16x16x32_bf16 v[64:67], v[186:189], v[240:243], v[64:67]
	s_barrier
	ds_read_b128 v[190:193], v169 offset:49152
	ds_read_b128 v[194:197], v169 offset:50176
	ds_read_b128 v[198:201], v169 offset:51200
	ds_read_b128 v[202:205], v169 offset:52224
	ds_read_b128 v[220:223], v169 offset:53248
	ds_read_b128 v[224:227], v169 offset:54272
	ds_read_b128 v[228:231], v169 offset:55296
	ds_read_b128 v[240:243], v169 offset:56320
	s_or_b32 s56, s55, 0x4000
	s_mov_b32 m0, s16
	s_nop 0
	buffer_load_dwordx4 v166, s[28:31], s56 offen lds
	s_add_i32 s55, s55, 0x84000
	s_mov_b32 m0, s17
	s_nop 0
	buffer_load_dwordx4 v167, s[28:31], s56 offen lds
	s_nop 0
	s_mov_b32 m0, s34
	s_nop 0
	buffer_load_dwordx4 v166, s[28:31], s55 offen lds
	s_nop 0
	s_mov_b32 m0, s40
	s_nop 0
	buffer_load_dwordx4 v167, s[28:31], s55 offen lds
	s_nop 0
	s_mov_b32 m0, s18
	s_nop 0
	buffer_load_dwordx4 v166, s[24:27], s53 offen lds
	s_nop 0
	s_mov_b32 m0, s19
	s_nop 0
	buffer_load_dwordx4 v167, s[24:27], s53 offen lds
	s_waitcnt vmcnt(8)
	s_waitcnt lgkmcnt(0)
	s_barrier
	v_mfma_f32_16x16x32_bf16 v[60:63], v[152:155], v[190:193], v[60:63]
	v_mfma_f32_16x16x32_bf16 v[52:55], v[160:163], v[190:193], v[52:55]
	v_mfma_f32_16x16x32_bf16 v[44:47], v[152:155], v[198:201], v[44:47]
	v_mfma_f32_16x16x32_bf16 v[36:39], v[160:163], v[198:201], v[36:39]
	v_mfma_f32_16x16x32_bf16 v[28:31], v[152:155], v[220:223], v[28:31]
	v_mfma_f32_16x16x32_bf16 v[20:23], v[160:163], v[220:223], v[20:23]
	v_mfma_f32_16x16x32_bf16 v[12:15], v[152:155], v[228:231], v[12:15]
	v_mfma_f32_16x16x32_bf16 v[4:7], v[160:163], v[228:231], v[4:7]
	v_mfma_f32_16x16x32_bf16 v[60:63], v[156:159], v[194:197], v[60:63]
	v_mfma_f32_16x16x32_bf16 v[52:55], v[170:173], v[194:197], v[52:55]
	v_mfma_f32_16x16x32_bf16 v[44:47], v[156:159], v[202:205], v[44:47]
	v_mfma_f32_16x16x32_bf16 v[36:39], v[170:173], v[202:205], v[36:39]
	v_mfma_f32_16x16x32_bf16 v[28:31], v[156:159], v[224:227], v[28:31]
	v_mfma_f32_16x16x32_bf16 v[20:23], v[170:173], v[224:227], v[20:23]
	v_mfma_f32_16x16x32_bf16 v[12:15], v[156:159], v[240:243], v[12:15]
	v_mfma_f32_16x16x32_bf16 v[4:7], v[170:173], v[240:243], v[4:7]
	v_mfma_f32_16x16x32_bf16 v[56:59], v[174:177], v[190:193], v[56:59]
	v_mfma_f32_16x16x32_bf16 v[48:51], v[182:185], v[190:193], v[48:51]
	v_mfma_f32_16x16x32_bf16 v[40:43], v[174:177], v[198:201], v[40:43]
	v_mfma_f32_16x16x32_bf16 v[32:35], v[182:185], v[198:201], v[32:35]
	v_mfma_f32_16x16x32_bf16 v[24:27], v[174:177], v[220:223], v[24:27]
	v_mfma_f32_16x16x32_bf16 v[16:19], v[182:185], v[220:223], v[16:19]
	v_mfma_f32_16x16x32_bf16 v[8:11], v[174:177], v[228:231], v[8:11]
	v_mfma_f32_16x16x32_bf16 v[0:3], v[182:185], v[228:231], v[0:3]
	v_mfma_f32_16x16x32_bf16 v[56:59], v[178:181], v[194:197], v[56:59]
	v_mfma_f32_16x16x32_bf16 v[48:51], v[186:189], v[194:197], v[48:51]
	v_mfma_f32_16x16x32_bf16 v[40:43], v[178:181], v[202:205], v[40:43]
	v_mfma_f32_16x16x32_bf16 v[32:35], v[186:189], v[202:205], v[32:35]
	v_mfma_f32_16x16x32_bf16 v[24:27], v[178:181], v[224:227], v[24:27]
	v_mfma_f32_16x16x32_bf16 v[16:19], v[186:189], v[224:227], v[16:19]
	v_mfma_f32_16x16x32_bf16 v[8:11], v[178:181], v[240:243], v[8:11]
	v_mfma_f32_16x16x32_bf16 v[0:3], v[186:189], v[240:243], v[0:3]
	s_barrier
	s_add_i32 s52, s52, 2
	s_add_i32 s37, s37, 0x8000
	s_add_i32 s51, s51, 0x8000
	s_cmp_gt_u32 s52, 29
	s_cbranch_scc0 .LBB0_795

.Lnb_p6:
	s_add_i32 s11, s8, 0xffea4000
	s_cmpk_eq_i32 s10, 0x54
	s_cselect_b32 s13, s6, s11
	s_cselect_b32 s12, s7, s9
	s_or_b32 s11, s13, 0x4000
	s_mov_b32 m0, s87
	s_nop 0
	buffer_load_dwordx4 v220, s[20:23], s8 offen lds
	s_nop 0
	s_mov_b32 m0, s89
	s_nop 0
	buffer_load_dwordx4 v221, s[20:23], s8 offen lds
	s_waitcnt vmcnt(24)
	s_waitcnt lgkmcnt(0)
	s_barrier
	v_mfma_f32_16x16x32_bf16 v[164:167], v[128:131], v[184:187], 0
	v_mfma_f32_16x16x32_bf16 v[160:163], v[152:155], v[184:187], 0
	v_mfma_f32_16x16x32_bf16 v[136:139], v[128:131], v[192:195], 0
	v_mfma_f32_16x16x32_bf16 v[132:135], v[152:155], v[192:195], 0
	v_mfma_f32_16x16x32_bf16 v[116:119], v[128:131], v[200:203], 0
	v_mfma_f32_16x16x32_bf16 v[112:115], v[152:155], v[200:203], 0
	v_mfma_f32_16x16x32_bf16 v[76:79], v[128:131], v[224:227], 0
	v_mfma_f32_16x16x32_bf16 v[72:75], v[152:155], v[224:227], 0
	v_mfma_f32_16x16x32_bf16 v[164:167], v[140:143], v[188:191], v[164:167]
	v_mfma_f32_16x16x32_bf16 v[160:163], v[156:159], v[188:191], v[160:163]
	v_mfma_f32_16x16x32_bf16 v[136:139], v[140:143], v[196:199], v[136:139]
	v_mfma_f32_16x16x32_bf16 v[132:135], v[156:159], v[196:199], v[132:135]
	v_mfma_f32_16x16x32_bf16 v[116:119], v[140:143], v[204:207], v[116:119]
	v_mfma_f32_16x16x32_bf16 v[112:115], v[156:159], v[204:207], v[112:115]
	v_mfma_f32_16x16x32_bf16 v[76:79], v[140:143], v[228:231], v[76:79]
	v_mfma_f32_16x16x32_bf16 v[72:75], v[156:159], v[228:231], v[72:75]
	v_mfma_f32_16x16x32_bf16 v[148:151], v[168:171], v[184:187], 0
	v_mfma_f32_16x16x32_bf16 v[144:147], v[176:179], v[184:187], 0
	v_mfma_f32_16x16x32_bf16 v[124:127], v[168:171], v[192:195], 0
	v_mfma_f32_16x16x32_bf16 v[120:123], v[176:179], v[192:195], 0
	v_mfma_f32_16x16x32_bf16 v[108:111], v[168:171], v[200:203], 0
	v_mfma_f32_16x16x32_bf16 v[104:107], v[176:179], v[200:203], 0
	v_mfma_f32_16x16x32_bf16 v[68:71], v[168:171], v[224:227], 0
	v_mfma_f32_16x16x32_bf16 v[64:67], v[176:179], v[224:227], 0
	v_mfma_f32_16x16x32_bf16 v[148:151], v[172:175], v[188:191], v[148:151]
	v_mfma_f32_16x16x32_bf16 v[144:147], v[180:183], v[188:191], v[144:147]
	v_mfma_f32_16x16x32_bf16 v[124:127], v[172:175], v[196:199], v[124:127]
	v_mfma_f32_16x16x32_bf16 v[120:123], v[180:183], v[196:199], v[120:123]
	v_mfma_f32_16x16x32_bf16 v[108:111], v[172:175], v[204:207], v[108:111]
	v_mfma_f32_16x16x32_bf16 v[104:107], v[180:183], v[204:207], v[104:107]
	v_mfma_f32_16x16x32_bf16 v[68:71], v[172:175], v[228:231], v[68:71]
	v_mfma_f32_16x16x32_bf16 v[64:67], v[180:183], v[228:231], v[64:67]
	s_barrier
	ds_read_b128 v[184:187], v223 offset:16384
	ds_read_b128 v[188:191], v223 offset:17408
	ds_read_b128 v[192:195], v223 offset:18432
	ds_read_b128 v[196:199], v223 offset:19456
	ds_read_b128 v[200:203], v223 offset:20480
	ds_read_b128 v[204:207], v223 offset:21504
	ds_read_b128 v[224:227], v223 offset:22528
	ds_read_b128 v[228:231], v223 offset:23552
	s_mov_b32 m0, s51
	s_nop 0
	buffer_load_dwordx4 v220, s[52:55], s12 offen lds
	s_add_i32 s14, s12, 0x160000
	s_mov_b32 m0, s74
	s_nop 0
	buffer_load_dwordx4 v221, s[52:55], s12 offen lds
	s_nop 0
	s_mov_b32 m0, s75
	s_nop 0
	buffer_load_dwordx4 v220, s[52:55], s14 offen lds
	s_nop 0
	s_mov_b32 m0, s76
	s_nop 0
	buffer_load_dwordx4 v221, s[52:55], s14 offen lds
	s_nop 0
	s_mov_b32 m0, s31
	s_nop 0
	buffer_load_dwordx4 v220, s[20:23], s13 offen lds
	s_nop 0
	s_mov_b32 m0, s77
	s_nop 0
	buffer_load_dwordx4 v221, s[20:23], s13 offen lds
	s_waitcnt vmcnt(24)
	s_waitcnt lgkmcnt(0)
	s_barrier
	v_mfma_f32_16x16x32_bf16 v[60:63], v[128:131], v[184:187], 0
	v_mfma_f32_16x16x32_bf16 v[56:59], v[152:155], v[184:187], 0
	v_mfma_f32_16x16x32_bf16 v[44:47], v[128:131], v[192:195], 0
	v_mfma_f32_16x16x32_bf16 v[40:43], v[152:155], v[192:195], 0
	v_mfma_f32_16x16x32_bf16 v[28:31], v[128:131], v[200:203], 0
	v_mfma_f32_16x16x32_bf16 v[24:27], v[152:155], v[200:203], 0
	v_mfma_f32_16x16x32_bf16 v[12:15], v[128:131], v[224:227], 0
	v_mfma_f32_16x16x32_bf16 v[8:11], v[152:155], v[224:227], 0
	v_mfma_f32_16x16x32_bf16 v[60:63], v[140:143], v[188:191], v[60:63]
	v_mfma_f32_16x16x32_bf16 v[56:59], v[156:159], v[188:191], v[56:59]
	v_mfma_f32_16x16x32_bf16 v[44:47], v[140:143], v[196:199], v[44:47]
	v_mfma_f32_16x16x32_bf16 v[40:43], v[156:159], v[196:199], v[40:43]
	v_mfma_f32_16x16x32_bf16 v[28:31], v[140:143], v[204:207], v[28:31]
	v_mfma_f32_16x16x32_bf16 v[24:27], v[156:159], v[204:207], v[24:27]
	v_mfma_f32_16x16x32_bf16 v[12:15], v[140:143], v[228:231], v[12:15]
	v_mfma_f32_16x16x32_bf16 v[8:11], v[156:159], v[228:231], v[8:11]
	v_mfma_f32_16x16x32_bf16 v[52:55], v[168:171], v[184:187], 0
	v_mfma_f32_16x16x32_bf16 v[48:51], v[176:179], v[184:187], 0
	v_mfma_f32_16x16x32_bf16 v[36:39], v[168:171], v[192:195], 0
	v_mfma_f32_16x16x32_bf16 v[32:35], v[176:179], v[192:195], 0
	v_mfma_f32_16x16x32_bf16 v[20:23], v[168:171], v[200:203], 0
	v_mfma_f32_16x16x32_bf16 v[16:19], v[176:179], v[200:203], 0
	v_mfma_f32_16x16x32_bf16 v[4:7], v[168:171], v[224:227], 0
	v_mfma_f32_16x16x32_bf16 v[0:3], v[176:179], v[224:227], 0
	v_mfma_f32_16x16x32_bf16 v[52:55], v[172:175], v[188:191], v[52:55]
	v_mfma_f32_16x16x32_bf16 v[48:51], v[180:183], v[188:191], v[48:51]
	v_mfma_f32_16x16x32_bf16 v[36:39], v[172:175], v[196:199], v[36:39]
	v_mfma_f32_16x16x32_bf16 v[32:35], v[180:183], v[196:199], v[32:35]
	v_mfma_f32_16x16x32_bf16 v[20:23], v[172:175], v[204:207], v[20:23]
	v_mfma_f32_16x16x32_bf16 v[16:19], v[180:183], v[204:207], v[16:19]
	v_mfma_f32_16x16x32_bf16 v[4:7], v[172:175], v[228:231], v[4:7]
	v_mfma_f32_16x16x32_bf16 v[0:3], v[180:183], v[228:231], v[0:3]
	s_barrier
	v_add_u32_e32 v156, 0x18000, v222
	v_add_u32_e32 v180, 0x1c000, v222
	ds_read_b128 v[128:131], v156
	ds_read_b128 v[140:143], v156 offset:1024
	ds_read_b128 v[152:155], v156 offset:2048
	ds_read_b128 v[156:159], v156 offset:3072
	ds_read_b128 v[168:171], v180
	ds_read_b128 v[172:175], v180 offset:1024
	ds_read_b128 v[176:179], v180 offset:2048
	ds_read_b128 v[180:183], v180 offset:3072
	ds_read_b128 v[184:187], v223 offset:32768
	ds_read_b128 v[188:191], v223 offset:33792
	ds_read_b128 v[192:195], v223 offset:34816
	ds_read_b128 v[196:199], v223 offset:35840
	ds_read_b128 v[200:203], v223 offset:36864
	ds_read_b128 v[204:207], v223 offset:37888
	ds_read_b128 v[224:227], v223 offset:38912
	ds_read_b128 v[228:231], v223 offset:39936
	s_add_i32 s13, s13, 0x160000
	s_mov_b32 m0, s78
	s_nop 0
	buffer_load_dwordx4 v220, s[20:23], s13 offen lds
	s_nop 0
	s_mov_b32 m0, s79
	s_nop 0
	buffer_load_dwordx4 v221, s[20:23], s13 offen lds
	s_waitcnt vmcnt(8)
	s_waitcnt lgkmcnt(0)
	s_barrier
	v_mfma_f32_16x16x32_bf16 v[164:167], v[128:131], v[184:187], v[164:167]
	v_mfma_f32_16x16x32_bf16 v[160:163], v[152:155], v[184:187], v[160:163]
	v_mfma_f32_16x16x32_bf16 v[136:139], v[128:131], v[192:195], v[136:139]
	v_mfma_f32_16x16x32_bf16 v[132:135], v[152:155], v[192:195], v[132:135]
	v_mfma_f32_16x16x32_bf16 v[116:119], v[128:131], v[200:203], v[116:119]
	v_mfma_f32_16x16x32_bf16 v[112:115], v[152:155], v[200:203], v[112:115]
	v_mfma_f32_16x16x32_bf16 v[76:79], v[128:131], v[224:227], v[76:79]
	v_mfma_f32_16x16x32_bf16 v[72:75], v[152:155], v[224:227], v[72:75]
	v_mfma_f32_16x16x32_bf16 v[164:167], v[140:143], v[188:191], v[164:167]
	v_mfma_f32_16x16x32_bf16 v[160:163], v[156:159], v[188:191], v[160:163]
	v_mfma_f32_16x16x32_bf16 v[136:139], v[140:143], v[196:199], v[136:139]
	v_mfma_f32_16x16x32_bf16 v[132:135], v[156:159], v[196:199], v[132:135]
	v_mfma_f32_16x16x32_bf16 v[116:119], v[140:143], v[204:207], v[116:119]
	v_mfma_f32_16x16x32_bf16 v[112:115], v[156:159], v[204:207], v[112:115]
	v_mfma_f32_16x16x32_bf16 v[76:79], v[140:143], v[228:231], v[76:79]
	v_mfma_f32_16x16x32_bf16 v[72:75], v[156:159], v[228:231], v[72:75]
	v_mfma_f32_16x16x32_bf16 v[148:151], v[168:171], v[184:187], v[148:151]
	v_mfma_f32_16x16x32_bf16 v[144:147], v[176:179], v[184:187], v[144:147]
	v_mfma_f32_16x16x32_bf16 v[124:127], v[168:171], v[192:195], v[124:127]
	v_mfma_f32_16x16x32_bf16 v[120:123], v[176:179], v[192:195], v[120:123]
	v_mfma_f32_16x16x32_bf16 v[108:111], v[168:171], v[200:203], v[108:111]
	v_mfma_f32_16x16x32_bf16 v[104:107], v[176:179], v[200:203], v[104:107]
	v_mfma_f32_16x16x32_bf16 v[68:71], v[168:171], v[224:227], v[68:71]
	v_mfma_f32_16x16x32_bf16 v[64:67], v[176:179], v[224:227], v[64:67]
	v_mfma_f32_16x16x32_bf16 v[148:151], v[172:175], v[188:191], v[148:151]
	v_mfma_f32_16x16x32_bf16 v[144:147], v[180:183], v[188:191], v[144:147]
	v_mfma_f32_16x16x32_bf16 v[124:127], v[172:175], v[196:199], v[124:127]
	v_mfma_f32_16x16x32_bf16 v[120:123], v[180:183], v[196:199], v[120:123]
	v_mfma_f32_16x16x32_bf16 v[108:111], v[172:175], v[204:207], v[108:111]
	v_mfma_f32_16x16x32_bf16 v[104:107], v[180:183], v[204:207], v[104:107]
	v_mfma_f32_16x16x32_bf16 v[68:71], v[172:175], v[228:231], v[68:71]
	v_mfma_f32_16x16x32_bf16 v[64:67], v[180:183], v[228:231], v[64:67]
	s_barrier
	ds_read_b128 v[184:187], v223 offset:49152
	ds_read_b128 v[188:191], v223 offset:50176
	ds_read_b128 v[192:195], v223 offset:51200
	ds_read_b128 v[196:199], v223 offset:52224
	ds_read_b128 v[200:203], v223 offset:53248
	ds_read_b128 v[204:207], v223 offset:54272
	ds_read_b128 v[224:227], v223 offset:55296
	ds_read_b128 v[228:231], v223 offset:56320
	s_or_b32 s13, s12, 0x4000
	s_mov_b32 m0, s34
	s_nop 0
	buffer_load_dwordx4 v220, s[52:55], s13 offen lds
	s_add_i32 s12, s12, 0x164000
	s_mov_b32 m0, s82
	s_nop 0
	buffer_load_dwordx4 v221, s[52:55], s13 offen lds
	s_nop 0
	s_mov_b32 m0, s85
	s_nop 0
	buffer_load_dwordx4 v220, s[52:55], s12 offen lds
	s_nop 0
	s_mov_b32 m0, s86
	s_nop 0
	buffer_load_dwordx4 v221, s[52:55], s12 offen lds
	s_nop 0
	s_mov_b32 m0, s83
	s_nop 0
	buffer_load_dwordx4 v220, s[20:23], s11 offen lds
	s_nop 0
	s_mov_b32 m0, s84
	s_nop 0
	buffer_load_dwordx4 v221, s[20:23], s11 offen lds
	s_waitcnt vmcnt(8)
	s_waitcnt lgkmcnt(0)
	s_barrier
	v_mfma_f32_16x16x32_bf16 v[60:63], v[128:131], v[184:187], v[60:63]
	v_mfma_f32_16x16x32_bf16 v[56:59], v[152:155], v[184:187], v[56:59]
	v_mfma_f32_16x16x32_bf16 v[44:47], v[128:131], v[192:195], v[44:47]
	v_mfma_f32_16x16x32_bf16 v[40:43], v[152:155], v[192:195], v[40:43]
	v_mfma_f32_16x16x32_bf16 v[28:31], v[128:131], v[200:203], v[28:31]
	v_mfma_f32_16x16x32_bf16 v[24:27], v[152:155], v[200:203], v[24:27]
	v_mfma_f32_16x16x32_bf16 v[12:15], v[128:131], v[224:227], v[12:15]
	v_mfma_f32_16x16x32_bf16 v[8:11], v[152:155], v[224:227], v[8:11]
	v_mfma_f32_16x16x32_bf16 v[60:63], v[140:143], v[188:191], v[60:63]
	v_mfma_f32_16x16x32_bf16 v[56:59], v[156:159], v[188:191], v[56:59]
	v_mfma_f32_16x16x32_bf16 v[44:47], v[140:143], v[196:199], v[44:47]
	v_mfma_f32_16x16x32_bf16 v[40:43], v[156:159], v[196:199], v[40:43]
	v_mfma_f32_16x16x32_bf16 v[28:31], v[140:143], v[204:207], v[28:31]
	v_mfma_f32_16x16x32_bf16 v[24:27], v[156:159], v[204:207], v[24:27]
	v_mfma_f32_16x16x32_bf16 v[12:15], v[140:143], v[228:231], v[12:15]
	v_mfma_f32_16x16x32_bf16 v[8:11], v[156:159], v[228:231], v[8:11]
	v_mfma_f32_16x16x32_bf16 v[52:55], v[168:171], v[184:187], v[52:55]
	v_mfma_f32_16x16x32_bf16 v[48:51], v[176:179], v[184:187], v[48:51]
	v_mfma_f32_16x16x32_bf16 v[36:39], v[168:171], v[192:195], v[36:39]
	v_mfma_f32_16x16x32_bf16 v[32:35], v[176:179], v[192:195], v[32:35]
	v_mfma_f32_16x16x32_bf16 v[20:23], v[168:171], v[200:203], v[20:23]
	v_mfma_f32_16x16x32_bf16 v[16:19], v[176:179], v[200:203], v[16:19]
	v_mfma_f32_16x16x32_bf16 v[4:7], v[168:171], v[224:227], v[4:7]
	v_mfma_f32_16x16x32_bf16 v[0:3], v[176:179], v[224:227], v[0:3]
	v_mfma_f32_16x16x32_bf16 v[52:55], v[172:175], v[188:191], v[52:55]
	v_mfma_f32_16x16x32_bf16 v[48:51], v[180:183], v[188:191], v[48:51]
	v_mfma_f32_16x16x32_bf16 v[36:39], v[172:175], v[196:199], v[36:39]
	v_mfma_f32_16x16x32_bf16 v[32:35], v[180:183], v[196:199], v[32:35]
	v_mfma_f32_16x16x32_bf16 v[20:23], v[172:175], v[204:207], v[20:23]
	v_mfma_f32_16x16x32_bf16 v[16:19], v[180:183], v[204:207], v[16:19]
	v_mfma_f32_16x16x32_bf16 v[4:7], v[172:175], v[228:231], v[4:7]
	v_mfma_f32_16x16x32_bf16 v[0:3], v[180:183], v[228:231], v[0:3]
	s_barrier
	s_add_i32 s10, s10, 2
	s_add_i32 s8, s8, 0x8000
	s_add_i32 s9, s9, 0x8000
.LBB0_885:
	v_add_u32_e32 v156, 0x10000, v222
	v_add_u32_e32 v180, 0x14000, v222
	ds_read_b128 v[128:131], v156
	ds_read_b128 v[140:143], v156 offset:1024
	ds_read_b128 v[152:155], v156 offset:2048
	ds_read_b128 v[156:159], v156 offset:3072
	ds_read_b128 v[168:171], v180
	ds_read_b128 v[172:175], v180 offset:1024
	ds_read_b128 v[176:179], v180 offset:2048
	ds_read_b128 v[180:183], v180 offset:3072
	s_add_i32 s11, s8, 0xffea4000
	s_cmpk_eq_i32 s10, 0x54
	s_cselect_b32 s13, s6, s11
	s_cselect_b32 s12, s7, s9
	s_or_b32 s11, s13, 0x4000
	ds_read_b128 v[184:187], v223
	ds_read_b128 v[188:191], v223 offset:1024
	ds_read_b128 v[192:195], v223 offset:2048
	ds_read_b128 v[196:199], v223 offset:3072
	ds_read_b128 v[200:203], v223 offset:4096
	ds_read_b128 v[204:207], v223 offset:5120
	ds_read_b128 v[224:227], v223 offset:6144
	ds_read_b128 v[228:231], v223 offset:7168
	s_mov_b32 m0, s87
	s_nop 0
	buffer_load_dwordx4 v220, s[20:23], s8 offen lds
	s_nop 0
	s_mov_b32 m0, s89
	s_nop 0
	buffer_load_dwordx4 v221, s[20:23], s8 offen lds
	s_waitcnt vmcnt(8)
	s_waitcnt lgkmcnt(0)
	s_barrier
	v_mfma_f32_16x16x32_bf16 v[164:167], v[128:131], v[184:187], v[164:167]
	v_mfma_f32_16x16x32_bf16 v[160:163], v[152:155], v[184:187], v[160:163]
	v_mfma_f32_16x16x32_bf16 v[136:139], v[128:131], v[192:195], v[136:139]
	v_mfma_f32_16x16x32_bf16 v[132:135], v[152:155], v[192:195], v[132:135]
	v_mfma_f32_16x16x32_bf16 v[116:119], v[128:131], v[200:203], v[116:119]
	v_mfma_f32_16x16x32_bf16 v[112:115], v[152:155], v[200:203], v[112:115]
	v_mfma_f32_16x16x32_bf16 v[76:79], v[128:131], v[224:227], v[76:79]
	v_mfma_f32_16x16x32_bf16 v[72:75], v[152:155], v[224:227], v[72:75]
	v_mfma_f32_16x16x32_bf16 v[164:167], v[140:143], v[188:191], v[164:167]
	v_mfma_f32_16x16x32_bf16 v[160:163], v[156:159], v[188:191], v[160:163]
	v_mfma_f32_16x16x32_bf16 v[136:139], v[140:143], v[196:199], v[136:139]
	v_mfma_f32_16x16x32_bf16 v[132:135], v[156:159], v[196:199], v[132:135]
	v_mfma_f32_16x16x32_bf16 v[116:119], v[140:143], v[204:207], v[116:119]
	v_mfma_f32_16x16x32_bf16 v[112:115], v[156:159], v[204:207], v[112:115]
	v_mfma_f32_16x16x32_bf16 v[76:79], v[140:143], v[228:231], v[76:79]
	v_mfma_f32_16x16x32_bf16 v[72:75], v[156:159], v[228:231], v[72:75]
	v_mfma_f32_16x16x32_bf16 v[148:151], v[168:171], v[184:187], v[148:151]
	v_mfma_f32_16x16x32_bf16 v[144:147], v[176:179], v[184:187], v[144:147]
	v_mfma_f32_16x16x32_bf16 v[124:127], v[168:171], v[192:195], v[124:127]
	v_mfma_f32_16x16x32_bf16 v[120:123], v[176:179], v[192:195], v[120:123]
	v_mfma_f32_16x16x32_bf16 v[108:111], v[168:171], v[200:203], v[108:111]
	v_mfma_f32_16x16x32_bf16 v[104:107], v[176:179], v[200:203], v[104:107]
	v_mfma_f32_16x16x32_bf16 v[68:71], v[168:171], v[224:227], v[68:71]
	v_mfma_f32_16x16x32_bf16 v[64:67], v[176:179], v[224:227], v[64:67]
	v_mfma_f32_16x16x32_bf16 v[148:151], v[172:175], v[188:191], v[148:151]
	v_mfma_f32_16x16x32_bf16 v[144:147], v[180:183], v[188:191], v[144:147]
	v_mfma_f32_16x16x32_bf16 v[124:127], v[172:175], v[196:199], v[124:127]
	v_mfma_f32_16x16x32_bf16 v[120:123], v[180:183], v[196:199], v[120:123]
	v_mfma_f32_16x16x32_bf16 v[108:111], v[172:175], v[204:207], v[108:111]
	v_mfma_f32_16x16x32_bf16 v[104:107], v[180:183], v[204:207], v[104:107]
	v_mfma_f32_16x16x32_bf16 v[68:71], v[172:175], v[228:231], v[68:71]
	v_mfma_f32_16x16x32_bf16 v[64:67], v[180:183], v[228:231], v[64:67]
	s_barrier
	ds_read_b128 v[184:187], v223 offset:16384
	ds_read_b128 v[188:191], v223 offset:17408
	ds_read_b128 v[192:195], v223 offset:18432
	ds_read_b128 v[196:199], v223 offset:19456
	ds_read_b128 v[200:203], v223 offset:20480
	ds_read_b128 v[204:207], v223 offset:21504
	ds_read_b128 v[224:227], v223 offset:22528
	ds_read_b128 v[228:231], v223 offset:23552
	s_mov_b32 m0, s51
	s_nop 0
	buffer_load_dwordx4 v220, s[52:55], s12 offen lds
	s_add_i32 s14, s12, 0x160000
	s_mov_b32 m0, s74
	s_nop 0
	buffer_load_dwordx4 v221, s[52:55], s12 offen lds
	s_nop 0
	s_mov_b32 m0, s75
	s_nop 0
	buffer_load_dwordx4 v220, s[52:55], s14 offen lds
	s_nop 0
	s_mov_b32 m0, s76
	s_nop 0
	buffer_load_dwordx4 v221, s[52:55], s14 offen lds
	s_nop 0
	s_mov_b32 m0, s31
	s_nop 0
	buffer_load_dwordx4 v220, s[20:23], s13 offen lds
	s_nop 0
	s_mov_b32 m0, s77
	s_nop 0
	buffer_load_dwordx4 v221, s[20:23], s13 offen lds
	s_waitcnt vmcnt(8)
	s_waitcnt lgkmcnt(0)
	s_barrier
	v_mfma_f32_16x16x32_bf16 v[60:63], v[128:131], v[184:187], v[60:63]
	v_mfma_f32_16x16x32_bf16 v[56:59], v[152:155], v[184:187], v[56:59]
	v_mfma_f32_16x16x32_bf16 v[44:47], v[128:131], v[192:195], v[44:47]
	v_mfma_f32_16x16x32_bf16 v[40:43], v[152:155], v[192:195], v[40:43]
	v_mfma_f32_16x16x32_bf16 v[28:31], v[128:131], v[200:203], v[28:31]
	v_mfma_f32_16x16x32_bf16 v[24:27], v[152:155], v[200:203], v[24:27]
	v_mfma_f32_16x16x32_bf16 v[12:15], v[128:131], v[224:227], v[12:15]
	v_mfma_f32_16x16x32_bf16 v[8:11], v[152:155], v[224:227], v[8:11]
	v_mfma_f32_16x16x32_bf16 v[60:63], v[140:143], v[188:191], v[60:63]
	v_mfma_f32_16x16x32_bf16 v[56:59], v[156:159], v[188:191], v[56:59]
	v_mfma_f32_16x16x32_bf16 v[44:47], v[140:143], v[196:199], v[44:47]
	v_mfma_f32_16x16x32_bf16 v[40:43], v[156:159], v[196:199], v[40:43]
	v_mfma_f32_16x16x32_bf16 v[28:31], v[140:143], v[204:207], v[28:31]
	v_mfma_f32_16x16x32_bf16 v[24:27], v[156:159], v[204:207], v[24:27]
	v_mfma_f32_16x16x32_bf16 v[12:15], v[140:143], v[228:231], v[12:15]
	v_mfma_f32_16x16x32_bf16 v[8:11], v[156:159], v[228:231], v[8:11]
	v_mfma_f32_16x16x32_bf16 v[52:55], v[168:171], v[184:187], v[52:55]
	v_mfma_f32_16x16x32_bf16 v[48:51], v[176:179], v[184:187], v[48:51]
	v_mfma_f32_16x16x32_bf16 v[36:39], v[168:171], v[192:195], v[36:39]
	v_mfma_f32_16x16x32_bf16 v[32:35], v[176:179], v[192:195], v[32:35]
	v_mfma_f32_16x16x32_bf16 v[20:23], v[168:171], v[200:203], v[20:23]
	v_mfma_f32_16x16x32_bf16 v[16:19], v[176:179], v[200:203], v[16:19]
	v_mfma_f32_16x16x32_bf16 v[4:7], v[168:171], v[224:227], v[4:7]
	v_mfma_f32_16x16x32_bf16 v[0:3], v[176:179], v[224:227], v[0:3]
	v_mfma_f32_16x16x32_bf16 v[52:55], v[172:175], v[188:191], v[52:55]
	v_mfma_f32_16x16x32_bf16 v[48:51], v[180:183], v[188:191], v[48:51]
	v_mfma_f32_16x16x32_bf16 v[36:39], v[172:175], v[196:199], v[36:39]
	v_mfma_f32_16x16x32_bf16 v[32:35], v[180:183], v[196:199], v[32:35]
	v_mfma_f32_16x16x32_bf16 v[20:23], v[172:175], v[204:207], v[20:23]
	v_mfma_f32_16x16x32_bf16 v[16:19], v[180:183], v[204:207], v[16:19]
	v_mfma_f32_16x16x32_bf16 v[4:7], v[172:175], v[228:231], v[4:7]
	v_mfma_f32_16x16x32_bf16 v[0:3], v[180:183], v[228:231], v[0:3]
	s_barrier
	v_add_u32_e32 v156, 0x18000, v222
	v_add_u32_e32 v180, 0x1c000, v222
	ds_read_b128 v[128:131], v156
	ds_read_b128 v[140:143], v156 offset:1024
	ds_read_b128 v[152:155], v156 offset:2048
	ds_read_b128 v[156:159], v156 offset:3072
	ds_read_b128 v[168:171], v180
	ds_read_b128 v[172:175], v180 offset:1024
	ds_read_b128 v[176:179], v180 offset:2048
	ds_read_b128 v[180:183], v180 offset:3072
	ds_read_b128 v[184:187], v223 offset:32768
	ds_read_b128 v[188:191], v223 offset:33792
	ds_read_b128 v[192:195], v223 offset:34816
	ds_read_b128 v[196:199], v223 offset:35840
	ds_read_b128 v[200:203], v223 offset:36864
	ds_read_b128 v[204:207], v223 offset:37888
	ds_read_b128 v[224:227], v223 offset:38912
	ds_read_b128 v[228:231], v223 offset:39936
	s_add_i32 s13, s13, 0x160000
	s_mov_b32 m0, s78
	s_nop 0
	buffer_load_dwordx4 v220, s[20:23], s13 offen lds
	s_nop 0
	s_mov_b32 m0, s79
	s_nop 0
	buffer_load_dwordx4 v221, s[20:23], s13 offen lds
	s_waitcnt vmcnt(8)
	s_waitcnt lgkmcnt(0)
	s_barrier
	v_mfma_f32_16x16x32_bf16 v[164:167], v[128:131], v[184:187], v[164:167]
	v_mfma_f32_16x16x32_bf16 v[160:163], v[152:155], v[184:187], v[160:163]
	v_mfma_f32_16x16x32_bf16 v[136:139], v[128:131], v[192:195], v[136:139]
	v_mfma_f32_16x16x32_bf16 v[132:135], v[152:155], v[192:195], v[132:135]
	v_mfma_f32_16x16x32_bf16 v[116:119], v[128:131], v[200:203], v[116:119]
	v_mfma_f32_16x16x32_bf16 v[112:115], v[152:155], v[200:203], v[112:115]
	v_mfma_f32_16x16x32_bf16 v[76:79], v[128:131], v[224:227], v[76:79]
	v_mfma_f32_16x16x32_bf16 v[72:75], v[152:155], v[224:227], v[72:75]
	v_mfma_f32_16x16x32_bf16 v[164:167], v[140:143], v[188:191], v[164:167]
	v_mfma_f32_16x16x32_bf16 v[160:163], v[156:159], v[188:191], v[160:163]
	v_mfma_f32_16x16x32_bf16 v[136:139], v[140:143], v[196:199], v[136:139]
	v_mfma_f32_16x16x32_bf16 v[132:135], v[156:159], v[196:199], v[132:135]
	v_mfma_f32_16x16x32_bf16 v[116:119], v[140:143], v[204:207], v[116:119]
	v_mfma_f32_16x16x32_bf16 v[112:115], v[156:159], v[204:207], v[112:115]
	v_mfma_f32_16x16x32_bf16 v[76:79], v[140:143], v[228:231], v[76:79]
	v_mfma_f32_16x16x32_bf16 v[72:75], v[156:159], v[228:231], v[72:75]
	v_mfma_f32_16x16x32_bf16 v[148:151], v[168:171], v[184:187], v[148:151]
	v_mfma_f32_16x16x32_bf16 v[144:147], v[176:179], v[184:187], v[144:147]
	v_mfma_f32_16x16x32_bf16 v[124:127], v[168:171], v[192:195], v[124:127]
	v_mfma_f32_16x16x32_bf16 v[120:123], v[176:179], v[192:195], v[120:123]
	v_mfma_f32_16x16x32_bf16 v[108:111], v[168:171], v[200:203], v[108:111]
	v_mfma_f32_16x16x32_bf16 v[104:107], v[176:179], v[200:203], v[104:107]
	v_mfma_f32_16x16x32_bf16 v[68:71], v[168:171], v[224:227], v[68:71]
	v_mfma_f32_16x16x32_bf16 v[64:67], v[176:179], v[224:227], v[64:67]
	v_mfma_f32_16x16x32_bf16 v[148:151], v[172:175], v[188:191], v[148:151]
	v_mfma_f32_16x16x32_bf16 v[144:147], v[180:183], v[188:191], v[144:147]
	v_mfma_f32_16x16x32_bf16 v[124:127], v[172:175], v[196:199], v[124:127]
	v_mfma_f32_16x16x32_bf16 v[120:123], v[180:183], v[196:199], v[120:123]
	v_mfma_f32_16x16x32_bf16 v[108:111], v[172:175], v[204:207], v[108:111]
	v_mfma_f32_16x16x32_bf16 v[104:107], v[180:183], v[204:207], v[104:107]
	v_mfma_f32_16x16x32_bf16 v[68:71], v[172:175], v[228:231], v[68:71]
	v_mfma_f32_16x16x32_bf16 v[64:67], v[180:183], v[228:231], v[64:67]
	s_barrier
	ds_read_b128 v[184:187], v223 offset:49152
	ds_read_b128 v[188:191], v223 offset:50176
	ds_read_b128 v[192:195], v223 offset:51200
	ds_read_b128 v[196:199], v223 offset:52224
	ds_read_b128 v[200:203], v223 offset:53248
	ds_read_b128 v[204:207], v223 offset:54272
	ds_read_b128 v[224:227], v223 offset:55296
	ds_read_b128 v[228:231], v223 offset:56320
	s_or_b32 s13, s12, 0x4000
	s_mov_b32 m0, s34
	s_nop 0
	buffer_load_dwordx4 v220, s[52:55], s13 offen lds
	s_add_i32 s12, s12, 0x164000
	s_mov_b32 m0, s82
	s_nop 0
	buffer_load_dwordx4 v221, s[52:55], s13 offen lds
	s_nop 0
	s_mov_b32 m0, s85
	s_nop 0
	buffer_load_dwordx4 v220, s[52:55], s12 offen lds
	s_nop 0
	s_mov_b32 m0, s86
	s_nop 0
	buffer_load_dwordx4 v221, s[52:55], s12 offen lds
	s_nop 0
	s_mov_b32 m0, s83
	s_nop 0
	buffer_load_dwordx4 v220, s[20:23], s11 offen lds
	s_nop 0
	s_mov_b32 m0, s84
	s_nop 0
	buffer_load_dwordx4 v221, s[20:23], s11 offen lds
	s_waitcnt vmcnt(8)
	s_waitcnt lgkmcnt(0)
	s_barrier
	v_mfma_f32_16x16x32_bf16 v[60:63], v[128:131], v[184:187], v[60:63]
	v_mfma_f32_16x16x32_bf16 v[56:59], v[152:155], v[184:187], v[56:59]
	v_mfma_f32_16x16x32_bf16 v[44:47], v[128:131], v[192:195], v[44:47]
	v_mfma_f32_16x16x32_bf16 v[40:43], v[152:155], v[192:195], v[40:43]
	v_mfma_f32_16x16x32_bf16 v[28:31], v[128:131], v[200:203], v[28:31]
	v_mfma_f32_16x16x32_bf16 v[24:27], v[152:155], v[200:203], v[24:27]
	v_mfma_f32_16x16x32_bf16 v[12:15], v[128:131], v[224:227], v[12:15]
	v_mfma_f32_16x16x32_bf16 v[8:11], v[152:155], v[224:227], v[8:11]
	v_mfma_f32_16x16x32_bf16 v[60:63], v[140:143], v[188:191], v[60:63]
	v_mfma_f32_16x16x32_bf16 v[56:59], v[156:159], v[188:191], v[56:59]
	v_mfma_f32_16x16x32_bf16 v[44:47], v[140:143], v[196:199], v[44:47]
	v_mfma_f32_16x16x32_bf16 v[40:43], v[156:159], v[196:199], v[40:43]
	v_mfma_f32_16x16x32_bf16 v[28:31], v[140:143], v[204:207], v[28:31]
	v_mfma_f32_16x16x32_bf16 v[24:27], v[156:159], v[204:207], v[24:27]
	v_mfma_f32_16x16x32_bf16 v[12:15], v[140:143], v[228:231], v[12:15]
	v_mfma_f32_16x16x32_bf16 v[8:11], v[156:159], v[228:231], v[8:11]
	v_mfma_f32_16x16x32_bf16 v[52:55], v[168:171], v[184:187], v[52:55]
	v_mfma_f32_16x16x32_bf16 v[48:51], v[176:179], v[184:187], v[48:51]
	v_mfma_f32_16x16x32_bf16 v[36:39], v[168:171], v[192:195], v[36:39]
	v_mfma_f32_16x16x32_bf16 v[32:35], v[176:179], v[192:195], v[32:35]
	v_mfma_f32_16x16x32_bf16 v[20:23], v[168:171], v[200:203], v[20:23]
	v_mfma_f32_16x16x32_bf16 v[16:19], v[176:179], v[200:203], v[16:19]
	v_mfma_f32_16x16x32_bf16 v[4:7], v[168:171], v[224:227], v[4:7]
	v_mfma_f32_16x16x32_bf16 v[0:3], v[176:179], v[224:227], v[0:3]
	v_mfma_f32_16x16x32_bf16 v[52:55], v[172:175], v[188:191], v[52:55]
	v_mfma_f32_16x16x32_bf16 v[48:51], v[180:183], v[188:191], v[48:51]
	v_mfma_f32_16x16x32_bf16 v[36:39], v[172:175], v[196:199], v[36:39]
	v_mfma_f32_16x16x32_bf16 v[32:35], v[180:183], v[196:199], v[32:35]
	v_mfma_f32_16x16x32_bf16 v[20:23], v[172:175], v[204:207], v[20:23]
	v_mfma_f32_16x16x32_bf16 v[16:19], v[180:183], v[204:207], v[16:19]
	v_mfma_f32_16x16x32_bf16 v[4:7], v[172:175], v[228:231], v[4:7]
	v_mfma_f32_16x16x32_bf16 v[0:3], v[180:183], v[228:231], v[0:3]
	s_barrier
	s_add_i32 s10, s10, 2
	s_add_i32 s8, s8, 0x8000
	s_add_i32 s9, s9, 0x8000
	s_cmpk_gt_u32 s10, 0x55
	s_cbranch_scc0 .LBB0_885
